# GEMM K-loops: redundant post-barrier s_waitcnt lgkmcnt(0) in front of each MFMA burst removed (28 sites)
# baseline (speedup 1.0000x reference)
; #define PG8_STAGE(bufoff, gbase, voff) do { _Pragma("unroll") for (int _i = 0; _i < 2; ++_i) \
;         __builtin_amdgcn_global_load_lds((const unsigned*)((const char*)(gbase) + (voff)[_i]), (PG8_LAS unsigned*)(lds + (bufoff) + ldsw + _i * 8192), 16, 0, 0); } while (0)
; #define PG8_LDA(dst, b, h) do { _Pragma("unroll") for (int m = 0; m < 4; ++m) _Pragma("unroll") for (int k = 0; k < 2; ++k) dst[m][k] = *(const PG8_LAS bf16x8*)(lds + PG8_SA(b, h) + aoff + m * 2048 + k * 1024); } while (0)
; #define PG8_LDB(dst, b, h) do { _Pragma("unroll") for (int n = 0; n < 2; ++n) _Pragma("unroll") for (int k = 0; k < 2; ++k) dst[n][k] = *(const PG8_LAS bf16x8*)(lds + PG8_SB(b, h) + boff + n * 2048 + k * 1024); } while (0)
; #define PG8_MMA(ai, bj, At, Bt) do { __builtin_amdgcn_s_setprio(1); _Pragma("unroll") for (int m = 0; m < 4; ++m) _Pragma("unroll") for (int n = 0; n < 2; ++n) _Pragma("unroll") for (int k = 0; k < 2; ++k) \
;         acc[ai][bj][m][n] = __builtin_amdgcn_mfma_f32_16x16x32_bf16(Bt[n][k], At[m][k], acc[ai][bj][m][n], 0, 0, 0); __builtin_amdgcn_s_setprio(0); } while (0)
; #define PG8_WAIT_V(n) asm volatile("s_waitcnt vmcnt(" #n ")" ::: "memory")
; #define PG8_WAIT_L(n) asm volatile("s_waitcnt lgkmcnt(" #n ")" ::: "memory")
; template <class Epi, class Sched, bool ALIGN_EPI = false, bool SP2 = false>
; __device__ __forceinline__ void gemm_phase(PG8_LAS unsigned char* lds, const Gemm g, const Sched& S, const Epi& E, int tid_in) {
;     ...
;             const bool last = (t == nt - 2);
;             const char* a1 = cA + (size_t)(t + 1) * kstep;
;             const char* a2 = last ? nA : cA + (size_t)(t + 2) * kstep; const char* b2 = last ? nB : cB + (size_t)(t + 2) * kstep;
;             const char* a3 = a2 + kstep; const char* b3 = b2 + kstep;
;             if (last && has_next) S.a_ready(nxt);
;             if constexpr (SP2) {
;             PG8_LDB(B0, 0, 0); PG8_LDB(B1, 0, 1); PG8_SCHED; PG8_LDA(At, 0, 0); PG8_STAGE(PG8_SA(1, 1), a1 + hstepA, voffA);
;             PG8_WAIT_V(8); PG8_WAIT_L(0); PG8_BAR; PG8_MMA(0, 0, At, B0); PG8_MMA(0, 1, At, B1); PG8_BAR; PG8_SCHED;
;             PG8_LDA(At, 0, 1); PG8_STAGE(PG8_SB(0, 0), b2, voffB); PG8_STAGE(PG8_SB(0, 1), b2 + hstep, voffB); PG8_STAGE(PG8_SA(0, 0), a2, voffA);
;             PG8_WAIT_V(8); PG8_WAIT_L(0); PG8_BAR; PG8_MMA(1, 0, At, B0); PG8_MMA(1, 1, At, B1); PG8_BAR; PG8_SCHED;
.LBB0_204:
	s_add_u32 s10, s2, 0xfffc0080
	s_addc_u32 s11, s3, -1
	s_add_i32 s28, 0, 0x10000
	s_cmp_eq_u32 s27, 12
	s_cselect_b32 s13, s15, s11
	s_cselect_b32 s12, s20, s10
	v_add_u32_e32 v156, s28, v159
	s_cselect_b32 s11, s21, s26
	s_cselect_b32 s10, s24, s25
	s_add_i32 s52, 0, 0x14000
	ds_read_b128 v[144:147], v156
	ds_read_b128 v[148:151], v156 offset:1024
	ds_read_b128 v[152:155], v156 offset:2048
	ds_read_b128 v[162:165], v156 offset:3072
	v_add_u32_e32 v156, s52, v159
	ds_read_b128 v[166:169], v156
	ds_read_b128 v[170:173], v156 offset:1024
	ds_read_b128 v[174:177], v156 offset:2048
	ds_read_b128 v[178:181], v156 offset:3072
	s_add_i32 m0, s35, 0xc000
	ds_read_b128 v[182:185], v160
	ds_read_b128 v[186:189], v160 offset:1024
	ds_read_b128 v[200:203], v160 offset:2048
	ds_read_b128 v[204:207], v160 offset:3072
	ds_read_b128 v[208:211], v160 offset:4096
	ds_read_b128 v[212:215], v160 offset:5120
	ds_read_b128 v[216:219], v160 offset:6144
	ds_read_b128 v[226:229], v160 offset:7168
	global_load_lds_dwordx4 v142, s[2:3]
	s_add_i32 m0, s35, 0xe000
	s_nop 0
	global_load_lds_dwordx4 v140, s[2:3]
	s_waitcnt vmcnt(8)
	s_waitcnt lgkmcnt(0)
	s_barrier
	s_setprio 1
	v_mfma_f32_16x16x32_bf16 v[124:127], v[144:147], v[182:185], v[124:127]
	v_mfma_f32_16x16x32_bf16 v[120:123], v[152:155], v[182:185], v[120:123]
	v_mfma_f32_16x16x32_bf16 v[108:111], v[144:147], v[200:203], v[108:111]
	v_mfma_f32_16x16x32_bf16 v[104:107], v[152:155], v[200:203], v[104:107]
	v_mfma_f32_16x16x32_bf16 v[92:95], v[144:147], v[208:211], v[92:95]
	v_mfma_f32_16x16x32_bf16 v[88:91], v[152:155], v[208:211], v[88:91]
	v_mfma_f32_16x16x32_bf16 v[76:79], v[144:147], v[216:219], v[76:79]
	v_mfma_f32_16x16x32_bf16 v[72:75], v[152:155], v[216:219], v[72:75]
	v_mfma_f32_16x16x32_bf16 v[124:127], v[148:151], v[186:189], v[124:127]
	v_mfma_f32_16x16x32_bf16 v[120:123], v[162:165], v[186:189], v[120:123]
	v_mfma_f32_16x16x32_bf16 v[108:111], v[148:151], v[204:207], v[108:111]
	v_mfma_f32_16x16x32_bf16 v[104:107], v[162:165], v[204:207], v[104:107]
	v_mfma_f32_16x16x32_bf16 v[92:95], v[148:151], v[212:215], v[92:95]
	v_mfma_f32_16x16x32_bf16 v[88:91], v[162:165], v[212:215], v[88:91]
	v_mfma_f32_16x16x32_bf16 v[76:79], v[148:151], v[226:229], v[76:79]
	v_mfma_f32_16x16x32_bf16 v[72:75], v[162:165], v[226:229], v[72:75]
	s_setprio 0
	s_setprio 1
	v_mfma_f32_16x16x32_bf16 v[116:119], v[166:169], v[182:185], v[116:119]
	v_mfma_f32_16x16x32_bf16 v[112:115], v[174:177], v[182:185], v[112:115]
	v_mfma_f32_16x16x32_bf16 v[100:103], v[166:169], v[200:203], v[100:103]
	v_mfma_f32_16x16x32_bf16 v[96:99], v[174:177], v[200:203], v[96:99]
	v_mfma_f32_16x16x32_bf16 v[84:87], v[166:169], v[208:211], v[84:87]
	v_mfma_f32_16x16x32_bf16 v[80:83], v[174:177], v[208:211], v[80:83]
	v_mfma_f32_16x16x32_bf16 v[68:71], v[166:169], v[216:219], v[68:71]
	v_mfma_f32_16x16x32_bf16 v[64:67], v[174:177], v[216:219], v[64:67]
	v_mfma_f32_16x16x32_bf16 v[116:119], v[170:173], v[186:189], v[116:119]
	v_mfma_f32_16x16x32_bf16 v[112:115], v[178:181], v[186:189], v[112:115]
	v_mfma_f32_16x16x32_bf16 v[100:103], v[170:173], v[204:207], v[100:103]
	v_mfma_f32_16x16x32_bf16 v[96:99], v[178:181], v[204:207], v[96:99]
	v_mfma_f32_16x16x32_bf16 v[84:87], v[170:173], v[212:215], v[84:87]
	v_mfma_f32_16x16x32_bf16 v[80:83], v[178:181], v[212:215], v[80:83]
	v_mfma_f32_16x16x32_bf16 v[68:71], v[170:173], v[226:229], v[68:71]
	v_mfma_f32_16x16x32_bf16 v[64:67], v[178:181], v[226:229], v[64:67]
	s_setprio 0
	s_barrier
	s_add_i32 s28, s28, s34
	s_mov_b32 m0, s28
	ds_read_b128 v[182:185], v160 offset:16384
	ds_read_b128 v[186:189], v160 offset:17408
	ds_read_b128 v[200:203], v160 offset:18432
	ds_read_b128 v[204:207], v160 offset:19456
	ds_read_b128 v[208:211], v160 offset:20480
	ds_read_b128 v[212:215], v160 offset:21504
	ds_read_b128 v[216:219], v160 offset:22528
	ds_read_b128 v[226:229], v160 offset:23552
	global_load_lds_dwordx4 v132, s[10:11]
	s_add_i32 m0, s28, 0x2000
	s_add_u32 s28, s10, 0x40000
	s_addc_u32 s29, s11, 0
	s_add_i32 s52, s52, s34
	global_load_lds_dwordx4 v128, s[10:11]
	s_mov_b32 m0, s52
	s_mov_b64 s[100:101], s[12:13]
	global_load_lds_dwordx4 v132, s[28:29]
	s_add_i32 m0, s52, 0x2000
	s_nop 0
	global_load_lds_dwordx4 v128, s[28:29]
	s_mov_b32 m0, s35
	s_nop 0
	global_load_lds_dwordx4 v134, s[100:101]
	s_mov_b32 m0, s38
	s_nop 0
	global_load_lds_dwordx4 v130, s[100:101]
	s_waitcnt vmcnt(8)
	s_waitcnt lgkmcnt(0)
	s_barrier
	s_setprio 1
	v_mfma_f32_16x16x32_bf16 v[60:63], v[144:147], v[182:185], v[60:63]
	v_mfma_f32_16x16x32_bf16 v[56:59], v[152:155], v[182:185], v[56:59]
	v_mfma_f32_16x16x32_bf16 v[44:47], v[144:147], v[200:203], v[44:47]
	v_mfma_f32_16x16x32_bf16 v[40:43], v[152:155], v[200:203], v[40:43]
	v_mfma_f32_16x16x32_bf16 v[28:31], v[144:147], v[208:211], v[28:31]
	v_mfma_f32_16x16x32_bf16 v[24:27], v[152:155], v[208:211], v[24:27]
	v_mfma_f32_16x16x32_bf16 v[12:15], v[144:147], v[216:219], v[12:15]
	v_mfma_f32_16x16x32_bf16 v[8:11], v[152:155], v[216:219], v[8:11]
	v_mfma_f32_16x16x32_bf16 v[60:63], v[148:151], v[186:189], v[60:63]
	v_mfma_f32_16x16x32_bf16 v[56:59], v[162:165], v[186:189], v[56:59]
	v_mfma_f32_16x16x32_bf16 v[44:47], v[148:151], v[204:207], v[44:47]
	v_mfma_f32_16x16x32_bf16 v[40:43], v[162:165], v[204:207], v[40:43]
	v_mfma_f32_16x16x32_bf16 v[28:31], v[148:151], v[212:215], v[28:31]
	v_mfma_f32_16x16x32_bf16 v[24:27], v[162:165], v[212:215], v[24:27]
	v_mfma_f32_16x16x32_bf16 v[12:15], v[148:151], v[226:229], v[12:15]
	v_mfma_f32_16x16x32_bf16 v[8:11], v[162:165], v[226:229], v[8:11]
	s_setprio 0
	s_setprio 1
	v_mfma_f32_16x16x32_bf16 v[52:55], v[166:169], v[182:185], v[52:55]
	v_mfma_f32_16x16x32_bf16 v[48:51], v[174:177], v[182:185], v[48:51]
	v_mfma_f32_16x16x32_bf16 v[36:39], v[166:169], v[200:203], v[36:39]
	v_mfma_f32_16x16x32_bf16 v[32:35], v[174:177], v[200:203], v[32:35]
	v_mfma_f32_16x16x32_bf16 v[20:23], v[166:169], v[208:211], v[20:23]
	v_mfma_f32_16x16x32_bf16 v[16:19], v[174:177], v[208:211], v[16:19]
	v_mfma_f32_16x16x32_bf16 v[4:7], v[166:169], v[216:219], v[4:7]
	v_mfma_f32_16x16x32_bf16 v[0:3], v[174:177], v[216:219], v[0:3]
	v_mfma_f32_16x16x32_bf16 v[52:55], v[170:173], v[186:189], v[52:55]
	v_mfma_f32_16x16x32_bf16 v[48:51], v[178:181], v[186:189], v[48:51]
	v_mfma_f32_16x16x32_bf16 v[36:39], v[170:173], v[204:207], v[36:39]
	v_mfma_f32_16x16x32_bf16 v[32:35], v[178:181], v[204:207], v[32:35]
	v_mfma_f32_16x16x32_bf16 v[20:23], v[170:173], v[212:215], v[20:23]
	v_mfma_f32_16x16x32_bf16 v[16:19], v[178:181], v[212:215], v[16:19]
	v_mfma_f32_16x16x32_bf16 v[4:7], v[170:173], v[226:229], v[4:7]
	v_mfma_f32_16x16x32_bf16 v[0:3], v[178:181], v[226:229], v[0:3]
	s_setprio 0
	s_barrier
; #define PG8_STAGE(bufoff, gbase, voff) do { _Pragma("unroll") for (int _i = 0; _i < 2; ++_i) \
;         __builtin_amdgcn_global_load_lds((const unsigned*)((const char*)(gbase) + (voff)[_i]), (PG8_LAS unsigned*)(lds + (bufoff) + ldsw + _i * 8192), 16, 0, 0); } while (0)
; #define PG8_LDA(dst, b, h) do { _Pragma("unroll") for (int m = 0; m < 4; ++m) _Pragma("unroll") for (int k = 0; k < 2; ++k) dst[m][k] = *(const PG8_LAS bf16x8*)(lds + PG8_SA(b, h) + aoff + m * 2048 + k * 1024); } while (0)
; #define PG8_LDB(dst, b, h) do { _Pragma("unroll") for (int n = 0; n < 2; ++n) _Pragma("unroll") for (int k = 0; k < 2; ++k) dst[n][k] = *(const PG8_LAS bf16x8*)(lds + PG8_SB(b, h) + boff + n * 2048 + k * 1024); } while (0)
; #define PG8_MMA(ai, bj, At, Bt) do { __builtin_amdgcn_s_setprio(1); _Pragma("unroll") for (int m = 0; m < 4; ++m) _Pragma("unroll") for (int n = 0; n < 2; ++n) _Pragma("unroll") for (int k = 0; k < 2; ++k) \
;         acc[ai][bj][m][n] = __builtin_amdgcn_mfma_f32_16x16x32_bf16(Bt[n][k], At[m][k], acc[ai][bj][m][n], 0, 0, 0); __builtin_amdgcn_s_setprio(0); } while (0)
; #define PG8_WAIT_V(n) asm volatile("s_waitcnt vmcnt(" #n ")" ::: "memory")
; #define PG8_WAIT_L(n) asm volatile("s_waitcnt lgkmcnt(" #n ")" ::: "memory")
; #define PG8_BAR __builtin_amdgcn_s_barrier()
; #define PG8_SCHED __builtin_amdgcn_sched_barrier(0)
; template <class Epi, class Sched, bool ALIGN_EPI = false, bool SP2 = false>
; __device__ __forceinline__ void gemm_phase(PG8_LAS unsigned char* lds, const Gemm g, const Sched& S, const Epi& E, int tid_in) {
;     ...
;             PG8_LDB(B0, 1, 0); PG8_LDB(B1, 1, 1); PG8_SCHED; PG8_LDA(At, 1, 0); PG8_STAGE(PG8_SA(0, 1), a2 + hstepA, voffA);
;             PG8_WAIT_V(8); PG8_WAIT_L(0); PG8_BAR; PG8_MMA(0, 0, At, B0); PG8_MMA(0, 1, At, B1); PG8_BAR; PG8_SCHED;
;             PG8_LDA(At, 1, 1); PG8_STAGE(PG8_SB(1, 0), b3, voffB); PG8_STAGE(PG8_SB(1, 1), b3 + hstep, voffB); PG8_STAGE(PG8_SA(1, 0), a3, voffA);
;             PG8_WAIT_V(8); PG8_WAIT_L(0); PG8_BAR; PG8_MMA(1, 0, At, B0); PG8_MMA(1, 1, At, B1); PG8_BAR; PG8_SCHED;
	s_add_i32 s28, 0, 0x18000
	v_add_u32_e32 v161, s28, v159
	s_add_i32 s29, 0, 0x1c000
	ds_read_b128 v[144:147], v161
	ds_read_b128 v[148:151], v161 offset:1024
	ds_read_b128 v[152:155], v161 offset:2048
	ds_read_b128 v[162:165], v161 offset:3072
	v_add_u32_e32 v161, s29, v159
	ds_read_b128 v[166:169], v161
	ds_read_b128 v[170:173], v161 offset:1024
	ds_read_b128 v[174:177], v161 offset:2048
	ds_read_b128 v[178:181], v161 offset:3072
	s_add_u32 s12, s12, 0x40000
	s_addc_u32 s13, s13, 0
	s_mov_b32 m0, s77
	ds_read_b128 v[182:185], v160 offset:32768
	ds_read_b128 v[186:189], v160 offset:33792
	ds_read_b128 v[200:203], v160 offset:34816
	ds_read_b128 v[204:207], v160 offset:35840
	ds_read_b128 v[208:211], v160 offset:36864
	ds_read_b128 v[212:215], v160 offset:37888
	ds_read_b128 v[216:219], v160 offset:38912
	ds_read_b128 v[226:229], v160 offset:39936
	global_load_lds_dwordx4 v134, s[12:13]
	s_mov_b32 m0, s78
	s_nop 0
	global_load_lds_dwordx4 v130, s[12:13]
	s_waitcnt vmcnt(8)
	s_waitcnt lgkmcnt(0)
	s_barrier
	s_setprio 1
	v_mfma_f32_16x16x32_bf16 v[124:127], v[144:147], v[182:185], v[124:127]
	v_mfma_f32_16x16x32_bf16 v[120:123], v[152:155], v[182:185], v[120:123]
	v_mfma_f32_16x16x32_bf16 v[108:111], v[144:147], v[200:203], v[108:111]
	v_mfma_f32_16x16x32_bf16 v[104:107], v[152:155], v[200:203], v[104:107]
	v_mfma_f32_16x16x32_bf16 v[92:95], v[144:147], v[208:211], v[92:95]
	v_mfma_f32_16x16x32_bf16 v[88:91], v[152:155], v[208:211], v[88:91]
	v_mfma_f32_16x16x32_bf16 v[76:79], v[144:147], v[216:219], v[76:79]
	v_mfma_f32_16x16x32_bf16 v[72:75], v[152:155], v[216:219], v[72:75]
	v_mfma_f32_16x16x32_bf16 v[124:127], v[148:151], v[186:189], v[124:127]
	v_mfma_f32_16x16x32_bf16 v[120:123], v[162:165], v[186:189], v[120:123]
	v_mfma_f32_16x16x32_bf16 v[108:111], v[148:151], v[204:207], v[108:111]
	v_mfma_f32_16x16x32_bf16 v[104:107], v[162:165], v[204:207], v[104:107]
	v_mfma_f32_16x16x32_bf16 v[92:95], v[148:151], v[212:215], v[92:95]
	v_mfma_f32_16x16x32_bf16 v[88:91], v[162:165], v[212:215], v[88:91]
	v_mfma_f32_16x16x32_bf16 v[76:79], v[148:151], v[226:229], v[76:79]
	v_mfma_f32_16x16x32_bf16 v[72:75], v[162:165], v[226:229], v[72:75]
	s_setprio 0
	s_setprio 1
	v_mfma_f32_16x16x32_bf16 v[116:119], v[166:169], v[182:185], v[116:119]
	v_mfma_f32_16x16x32_bf16 v[112:115], v[174:177], v[182:185], v[112:115]
	v_mfma_f32_16x16x32_bf16 v[100:103], v[166:169], v[200:203], v[100:103]
	v_mfma_f32_16x16x32_bf16 v[96:99], v[174:177], v[200:203], v[96:99]
	v_mfma_f32_16x16x32_bf16 v[84:87], v[166:169], v[208:211], v[84:87]
	v_mfma_f32_16x16x32_bf16 v[80:83], v[174:177], v[208:211], v[80:83]
	v_mfma_f32_16x16x32_bf16 v[68:71], v[166:169], v[216:219], v[68:71]
	v_mfma_f32_16x16x32_bf16 v[64:67], v[174:177], v[216:219], v[64:67]
	v_mfma_f32_16x16x32_bf16 v[116:119], v[170:173], v[186:189], v[116:119]
	v_mfma_f32_16x16x32_bf16 v[112:115], v[178:181], v[186:189], v[112:115]
	v_mfma_f32_16x16x32_bf16 v[100:103], v[170:173], v[204:207], v[100:103]
	v_mfma_f32_16x16x32_bf16 v[96:99], v[178:181], v[204:207], v[96:99]
	v_mfma_f32_16x16x32_bf16 v[84:87], v[170:173], v[212:215], v[84:87]
	v_mfma_f32_16x16x32_bf16 v[80:83], v[178:181], v[212:215], v[80:83]
	v_mfma_f32_16x16x32_bf16 v[68:71], v[170:173], v[226:229], v[68:71]
	v_mfma_f32_16x16x32_bf16 v[64:67], v[178:181], v[226:229], v[64:67]
	s_setprio 0
	s_barrier
	s_add_i32 s12, s28, s34
	s_mov_b32 m0, s12
	ds_read_b128 v[182:185], v160 offset:49152
	ds_read_b128 v[186:189], v160 offset:50176
	ds_read_b128 v[200:203], v160 offset:51200
	ds_read_b128 v[204:207], v160 offset:52224
	ds_read_b128 v[208:211], v160 offset:53248
	ds_read_b128 v[212:215], v160 offset:54272
	ds_read_b128 v[216:219], v160 offset:55296
	ds_read_b128 v[226:229], v160 offset:56320
	s_add_u32 s10, s10, 0x80
	s_addc_u32 s11, s11, 0
	global_load_lds_dwordx4 v132, s[10:11]
	s_add_i32 m0, s12, 0x2000
	s_nop 0
	global_load_lds_dwordx4 v128, s[10:11]
	s_add_u32 s10, s10, 0x40000
	s_addc_u32 s11, s11, 0
	s_add_i32 s12, s29, s34
	s_mov_b32 m0, s12
	s_nop 0
	global_load_lds_dwordx4 v132, s[10:11]
	s_add_i32 m0, s12, 0x2000
	s_nop 0
	global_load_lds_dwordx4 v128, s[10:11]
	s_mov_b32 m0, s83
	s_nop 0
	s_add_u32 s100, s100, 0x80
	s_addc_u32 s101, s101, 0
	global_load_lds_dwordx4 v134, s[100:101]
	s_mov_b32 m0, s84
	s_nop 0
	global_load_lds_dwordx4 v130, s[100:101]
	s_waitcnt vmcnt(8)
	s_waitcnt lgkmcnt(0)
	s_barrier
	s_setprio 1
	v_mfma_f32_16x16x32_bf16 v[60:63], v[144:147], v[182:185], v[60:63]
	v_mfma_f32_16x16x32_bf16 v[56:59], v[152:155], v[182:185], v[56:59]
	v_mfma_f32_16x16x32_bf16 v[44:47], v[144:147], v[200:203], v[44:47]
	v_mfma_f32_16x16x32_bf16 v[40:43], v[152:155], v[200:203], v[40:43]
	v_mfma_f32_16x16x32_bf16 v[28:31], v[144:147], v[208:211], v[28:31]
	v_mfma_f32_16x16x32_bf16 v[24:27], v[152:155], v[208:211], v[24:27]
	v_mfma_f32_16x16x32_bf16 v[12:15], v[144:147], v[216:219], v[12:15]
	v_mfma_f32_16x16x32_bf16 v[8:11], v[152:155], v[216:219], v[8:11]
	v_mfma_f32_16x16x32_bf16 v[60:63], v[148:151], v[186:189], v[60:63]
	v_mfma_f32_16x16x32_bf16 v[56:59], v[162:165], v[186:189], v[56:59]
	v_mfma_f32_16x16x32_bf16 v[44:47], v[148:151], v[204:207], v[44:47]
	v_mfma_f32_16x16x32_bf16 v[40:43], v[162:165], v[204:207], v[40:43]
	v_mfma_f32_16x16x32_bf16 v[28:31], v[148:151], v[212:215], v[28:31]
	v_mfma_f32_16x16x32_bf16 v[24:27], v[162:165], v[212:215], v[24:27]
	v_mfma_f32_16x16x32_bf16 v[12:15], v[148:151], v[226:229], v[12:15]
	v_mfma_f32_16x16x32_bf16 v[8:11], v[162:165], v[226:229], v[8:11]
	s_setprio 0
	s_setprio 1
	v_mfma_f32_16x16x32_bf16 v[52:55], v[166:169], v[182:185], v[52:55]
	v_mfma_f32_16x16x32_bf16 v[48:51], v[174:177], v[182:185], v[48:51]
	v_mfma_f32_16x16x32_bf16 v[36:39], v[166:169], v[200:203], v[36:39]
	v_mfma_f32_16x16x32_bf16 v[32:35], v[174:177], v[200:203], v[32:35]
	v_mfma_f32_16x16x32_bf16 v[20:23], v[166:169], v[208:211], v[20:23]
	v_mfma_f32_16x16x32_bf16 v[16:19], v[174:177], v[208:211], v[16:19]
	v_mfma_f32_16x16x32_bf16 v[4:7], v[166:169], v[216:219], v[4:7]
	v_mfma_f32_16x16x32_bf16 v[0:3], v[174:177], v[216:219], v[0:3]
	v_mfma_f32_16x16x32_bf16 v[52:55], v[170:173], v[186:189], v[52:55]
	v_mfma_f32_16x16x32_bf16 v[48:51], v[178:181], v[186:189], v[48:51]
	v_mfma_f32_16x16x32_bf16 v[36:39], v[170:173], v[204:207], v[36:39]
	v_mfma_f32_16x16x32_bf16 v[32:35], v[178:181], v[204:207], v[32:35]
	v_mfma_f32_16x16x32_bf16 v[20:23], v[170:173], v[212:215], v[20:23]
	v_mfma_f32_16x16x32_bf16 v[16:19], v[178:181], v[212:215], v[16:19]
	v_mfma_f32_16x16x32_bf16 v[4:7], v[170:173], v[226:229], v[4:7]
	v_mfma_f32_16x16x32_bf16 v[0:3], v[178:181], v[226:229], v[0:3]
	s_setprio 0
	s_barrier
	s_add_i32 s27, s27, 2
	s_add_u32 s25, s25, 0x100
	s_addc_u32 s26, s26, 0
	s_add_u32 s2, s2, 0x100
	s_addc_u32 s3, s3, 0
	s_cmp_gt_u32 s27, 13
	s_cbranch_scc0 .LBB0_204
	s_and_b64 vcc, exec, s[62:63]
	s_cbranch_vccz .LBB0_207
	s_barrier

; #define PG8_STAGE(bufoff, gbase, voff) do { _Pragma("unroll") for (int _i = 0; _i < 2; ++_i) \
;         __builtin_amdgcn_global_load_lds((const unsigned*)((const char*)(gbase) + (voff)[_i]), (PG8_LAS unsigned*)(lds + (bufoff) + ldsw + _i * 8192), 16, 0, 0); } while (0)
; #define PG8_LDA(dst, b, h) do { _Pragma("unroll") for (int m = 0; m < 4; ++m) _Pragma("unroll") for (int k = 0; k < 2; ++k) dst[m][k] = *(const PG8_LAS bf16x8*)(lds + PG8_SA(b, h) + aoff + m * 2048 + k * 1024); } while (0)
; #define PG8_LDB(dst, b, h) do { _Pragma("unroll") for (int n = 0; n < 2; ++n) _Pragma("unroll") for (int k = 0; k < 2; ++k) dst[n][k] = *(const PG8_LAS bf16x8*)(lds + PG8_SB(b, h) + boff + n * 2048 + k * 1024); } while (0)
; #define PG8_MMA(ai, bj, At, Bt) do { __builtin_amdgcn_s_setprio(1); _Pragma("unroll") for (int m = 0; m < 4; ++m) _Pragma("unroll") for (int n = 0; n < 2; ++n) _Pragma("unroll") for (int k = 0; k < 2; ++k) \
;         acc[ai][bj][m][n] = __builtin_amdgcn_mfma_f32_16x16x32_bf16(Bt[n][k], At[m][k], acc[ai][bj][m][n], 0, 0, 0); __builtin_amdgcn_s_setprio(0); } while (0)
; #define PG8_WAIT_V(n) asm volatile("s_waitcnt vmcnt(" #n ")" ::: "memory")
; #define PG8_WAIT_L(n) asm volatile("s_waitcnt lgkmcnt(" #n ")" ::: "memory")
; template <class Epi, class Sched, bool ALIGN_EPI = false, bool SP2 = false>
; __device__ __forceinline__ void gemm_phase(PG8_LAS unsigned char* lds, const Gemm g, const Sched& S, const Epi& E, int tid_in) {
;     ...
;             const bool last = (t == nt - 2);
;             const char* a1 = cA + (size_t)(t + 1) * kstep;
;             const char* a2 = last ? nA : cA + (size_t)(t + 2) * kstep; const char* b2 = last ? nB : cB + (size_t)(t + 2) * kstep;
;             const char* a3 = a2 + kstep; const char* b3 = b2 + kstep;
;             if (last && has_next) S.a_ready(nxt);
;             if constexpr (SP2) {
;             PG8_LDB(B0, 0, 0); PG8_LDB(B1, 0, 1); PG8_SCHED; PG8_LDA(At, 0, 0); PG8_STAGE(PG8_SA(1, 1), a1 + hstepA, voffA);
;             PG8_WAIT_V(8); PG8_WAIT_L(0); PG8_BAR; PG8_MMA(0, 0, At, B0); PG8_MMA(0, 1, At, B1); PG8_BAR; PG8_SCHED;
;             PG8_LDA(At, 0, 1); PG8_STAGE(PG8_SB(0, 0), b2, voffB); PG8_STAGE(PG8_SB(0, 1), b2 + hstep, voffB); PG8_STAGE(PG8_SA(0, 0), a2, voffA);
;             PG8_WAIT_V(8); PG8_WAIT_L(0); PG8_BAR; PG8_MMA(1, 0, At, B0); PG8_MMA(1, 1, At, B1); PG8_BAR; PG8_SCHED;
.LBB0_526:
	s_add_u32 s12, s2, 0xfffc0080
	s_addc_u32 s13, s3, -1
	s_add_i32 s66, 0, 0x10000
	s_cmp_eq_u32 s65, 12
	s_cselect_b32 s15, s45, s13
	s_cselect_b32 s14, s46, s12
	v_add_u32_e32 v148, s66, v151
	s_cselect_b32 s13, s29, s64
	s_cselect_b32 s12, s47, s51
	s_add_i32 s68, 0, 0x14000
	ds_read_b128 v[140:143], v148
	ds_read_b128 v[144:147], v148 offset:1024
	ds_read_b128 v[160:163], v148 offset:2048
	ds_read_b128 v[164:167], v148 offset:3072
	v_add_u32_e32 v148, s68, v151
	ds_read_b128 v[168:171], v148
	ds_read_b128 v[172:175], v148 offset:1024
	ds_read_b128 v[176:179], v148 offset:2048
	ds_read_b128 v[180:183], v148 offset:3072
	s_add_i32 m0, s56, 0xc000
	ds_read_b128 v[184:187], v156
	ds_read_b128 v[200:203], v156 offset:1024
	ds_read_b128 v[204:207], v156 offset:2048
	ds_read_b128 v[208:211], v156 offset:3072
	ds_read_b128 v[212:215], v156 offset:4096
	ds_read_b128 v[216:219], v156 offset:5120
	ds_read_b128 v[226:229], v156 offset:6144
	ds_read_b128 v[230:233], v156 offset:7168
	global_load_lds_dwordx4 v138, s[2:3]
	s_add_i32 m0, s56, 0xe000
	s_nop 0
	global_load_lds_dwordx4 v136, s[2:3]
	s_waitcnt vmcnt(8)
	s_waitcnt lgkmcnt(0)
	s_barrier
	s_setprio 1
	v_mfma_f32_16x16x32_bf16 v[124:127], v[140:143], v[184:187], v[124:127]
	v_mfma_f32_16x16x32_bf16 v[120:123], v[160:163], v[184:187], v[120:123]
	v_mfma_f32_16x16x32_bf16 v[108:111], v[140:143], v[204:207], v[108:111]
	v_mfma_f32_16x16x32_bf16 v[104:107], v[160:163], v[204:207], v[104:107]
	v_mfma_f32_16x16x32_bf16 v[92:95], v[140:143], v[212:215], v[92:95]
	v_mfma_f32_16x16x32_bf16 v[88:91], v[160:163], v[212:215], v[88:91]
	v_mfma_f32_16x16x32_bf16 v[76:79], v[140:143], v[226:229], v[76:79]
	v_mfma_f32_16x16x32_bf16 v[72:75], v[160:163], v[226:229], v[72:75]
	v_mfma_f32_16x16x32_bf16 v[124:127], v[144:147], v[200:203], v[124:127]
	v_mfma_f32_16x16x32_bf16 v[120:123], v[164:167], v[200:203], v[120:123]
	v_mfma_f32_16x16x32_bf16 v[108:111], v[144:147], v[208:211], v[108:111]
	v_mfma_f32_16x16x32_bf16 v[104:107], v[164:167], v[208:211], v[104:107]
	v_mfma_f32_16x16x32_bf16 v[92:95], v[144:147], v[216:219], v[92:95]
	v_mfma_f32_16x16x32_bf16 v[88:91], v[164:167], v[216:219], v[88:91]
	v_mfma_f32_16x16x32_bf16 v[76:79], v[144:147], v[230:233], v[76:79]
	v_mfma_f32_16x16x32_bf16 v[72:75], v[164:167], v[230:233], v[72:75]
	s_setprio 0
	s_setprio 1
	v_mfma_f32_16x16x32_bf16 v[116:119], v[168:171], v[184:187], v[116:119]
	v_mfma_f32_16x16x32_bf16 v[112:115], v[176:179], v[184:187], v[112:115]
	v_mfma_f32_16x16x32_bf16 v[100:103], v[168:171], v[204:207], v[100:103]
	v_mfma_f32_16x16x32_bf16 v[96:99], v[176:179], v[204:207], v[96:99]
	v_mfma_f32_16x16x32_bf16 v[84:87], v[168:171], v[212:215], v[84:87]
	v_mfma_f32_16x16x32_bf16 v[80:83], v[176:179], v[212:215], v[80:83]
	v_mfma_f32_16x16x32_bf16 v[68:71], v[168:171], v[226:229], v[68:71]
	v_mfma_f32_16x16x32_bf16 v[64:67], v[176:179], v[226:229], v[64:67]
	v_mfma_f32_16x16x32_bf16 v[116:119], v[172:175], v[200:203], v[116:119]
	v_mfma_f32_16x16x32_bf16 v[112:115], v[180:183], v[200:203], v[112:115]
	v_mfma_f32_16x16x32_bf16 v[100:103], v[172:175], v[208:211], v[100:103]
	v_mfma_f32_16x16x32_bf16 v[96:99], v[180:183], v[208:211], v[96:99]
	v_mfma_f32_16x16x32_bf16 v[84:87], v[172:175], v[216:219], v[84:87]
	v_mfma_f32_16x16x32_bf16 v[80:83], v[180:183], v[216:219], v[80:83]
	v_mfma_f32_16x16x32_bf16 v[68:71], v[172:175], v[230:233], v[68:71]
	v_mfma_f32_16x16x32_bf16 v[64:67], v[180:183], v[230:233], v[64:67]
	s_setprio 0
	s_barrier
	s_add_i32 s66, s66, s49
	s_mov_b32 m0, s66
	ds_read_b128 v[184:187], v156 offset:16384
	ds_read_b128 v[200:203], v156 offset:17408
	ds_read_b128 v[204:207], v156 offset:18432
	ds_read_b128 v[208:211], v156 offset:19456
	ds_read_b128 v[212:215], v156 offset:20480
	ds_read_b128 v[216:219], v156 offset:21504
	ds_read_b128 v[226:229], v156 offset:22528
	ds_read_b128 v[230:233], v156 offset:23552
	global_load_lds_dwordx4 v132, s[12:13]
	s_add_i32 m0, s66, 0x2000
	s_add_u32 s66, s12, 0x40000
	s_addc_u32 s67, s13, 0
	s_add_i32 s68, s68, s49
	global_load_lds_dwordx4 v128, s[12:13]
	s_mov_b32 m0, s68
	s_mov_b64 s[100:101], s[14:15]
	global_load_lds_dwordx4 v132, s[66:67]
	s_add_i32 m0, s68, 0x2000
	s_nop 0
	global_load_lds_dwordx4 v128, s[66:67]
	s_mov_b32 m0, s56
	s_nop 0
	global_load_lds_dwordx4 v134, s[100:101]
	s_mov_b32 m0, s57
	s_nop 0
	global_load_lds_dwordx4 v130, s[100:101]
	s_waitcnt vmcnt(8)
	s_waitcnt lgkmcnt(0)
	s_barrier
	s_setprio 1
	v_mfma_f32_16x16x32_bf16 v[60:63], v[140:143], v[184:187], v[60:63]
	v_mfma_f32_16x16x32_bf16 v[56:59], v[160:163], v[184:187], v[56:59]
	v_mfma_f32_16x16x32_bf16 v[44:47], v[140:143], v[204:207], v[44:47]
	v_mfma_f32_16x16x32_bf16 v[40:43], v[160:163], v[204:207], v[40:43]
	v_mfma_f32_16x16x32_bf16 v[28:31], v[140:143], v[212:215], v[28:31]
	v_mfma_f32_16x16x32_bf16 v[24:27], v[160:163], v[212:215], v[24:27]
	v_mfma_f32_16x16x32_bf16 v[12:15], v[140:143], v[226:229], v[12:15]
	v_mfma_f32_16x16x32_bf16 v[8:11], v[160:163], v[226:229], v[8:11]
	v_mfma_f32_16x16x32_bf16 v[60:63], v[144:147], v[200:203], v[60:63]
	v_mfma_f32_16x16x32_bf16 v[56:59], v[164:167], v[200:203], v[56:59]
	v_mfma_f32_16x16x32_bf16 v[44:47], v[144:147], v[208:211], v[44:47]
	v_mfma_f32_16x16x32_bf16 v[40:43], v[164:167], v[208:211], v[40:43]
	v_mfma_f32_16x16x32_bf16 v[28:31], v[144:147], v[216:219], v[28:31]
	v_mfma_f32_16x16x32_bf16 v[24:27], v[164:167], v[216:219], v[24:27]
	v_mfma_f32_16x16x32_bf16 v[12:15], v[144:147], v[230:233], v[12:15]
	v_mfma_f32_16x16x32_bf16 v[8:11], v[164:167], v[230:233], v[8:11]
	s_setprio 0
	s_setprio 1
	v_mfma_f32_16x16x32_bf16 v[52:55], v[168:171], v[184:187], v[52:55]
	v_mfma_f32_16x16x32_bf16 v[48:51], v[176:179], v[184:187], v[48:51]
	v_mfma_f32_16x16x32_bf16 v[36:39], v[168:171], v[204:207], v[36:39]
	v_mfma_f32_16x16x32_bf16 v[32:35], v[176:179], v[204:207], v[32:35]
	v_mfma_f32_16x16x32_bf16 v[20:23], v[168:171], v[212:215], v[20:23]
	v_mfma_f32_16x16x32_bf16 v[16:19], v[176:179], v[212:215], v[16:19]
	v_mfma_f32_16x16x32_bf16 v[4:7], v[168:171], v[226:229], v[4:7]
	v_mfma_f32_16x16x32_bf16 v[0:3], v[176:179], v[226:229], v[0:3]
	v_mfma_f32_16x16x32_bf16 v[52:55], v[172:175], v[200:203], v[52:55]
	v_mfma_f32_16x16x32_bf16 v[48:51], v[180:183], v[200:203], v[48:51]
	v_mfma_f32_16x16x32_bf16 v[36:39], v[172:175], v[208:211], v[36:39]
	v_mfma_f32_16x16x32_bf16 v[32:35], v[180:183], v[208:211], v[32:35]
	v_mfma_f32_16x16x32_bf16 v[20:23], v[172:175], v[216:219], v[20:23]
	v_mfma_f32_16x16x32_bf16 v[16:19], v[180:183], v[216:219], v[16:19]
	v_mfma_f32_16x16x32_bf16 v[4:7], v[172:175], v[230:233], v[4:7]
	v_mfma_f32_16x16x32_bf16 v[0:3], v[180:183], v[230:233], v[0:3]
	s_setprio 0
	s_barrier
; #define PG8_STAGE(bufoff, gbase, voff) do { _Pragma("unroll") for (int _i = 0; _i < 2; ++_i) \
;         __builtin_amdgcn_global_load_lds((const unsigned*)((const char*)(gbase) + (voff)[_i]), (PG8_LAS unsigned*)(lds + (bufoff) + ldsw + _i * 8192), 16, 0, 0); } while (0)
; #define PG8_LDA(dst, b, h) do { _Pragma("unroll") for (int m = 0; m < 4; ++m) _Pragma("unroll") for (int k = 0; k < 2; ++k) dst[m][k] = *(const PG8_LAS bf16x8*)(lds + PG8_SA(b, h) + aoff + m * 2048 + k * 1024); } while (0)
; #define PG8_LDB(dst, b, h) do { _Pragma("unroll") for (int n = 0; n < 2; ++n) _Pragma("unroll") for (int k = 0; k < 2; ++k) dst[n][k] = *(const PG8_LAS bf16x8*)(lds + PG8_SB(b, h) + boff + n * 2048 + k * 1024); } while (0)
; #define PG8_MMA(ai, bj, At, Bt) do { __builtin_amdgcn_s_setprio(1); _Pragma("unroll") for (int m = 0; m < 4; ++m) _Pragma("unroll") for (int n = 0; n < 2; ++n) _Pragma("unroll") for (int k = 0; k < 2; ++k) \
;         acc[ai][bj][m][n] = __builtin_amdgcn_mfma_f32_16x16x32_bf16(Bt[n][k], At[m][k], acc[ai][bj][m][n], 0, 0, 0); __builtin_amdgcn_s_setprio(0); } while (0)
; #define PG8_WAIT_V(n) asm volatile("s_waitcnt vmcnt(" #n ")" ::: "memory")
; #define PG8_WAIT_L(n) asm volatile("s_waitcnt lgkmcnt(" #n ")" ::: "memory")
; #define PG8_BAR __builtin_amdgcn_s_barrier()
; #define PG8_SCHED __builtin_amdgcn_sched_barrier(0)
; template <class Epi, class Sched, bool ALIGN_EPI = false, bool SP2 = false>
; __device__ __forceinline__ void gemm_phase(PG8_LAS unsigned char* lds, const Gemm g, const Sched& S, const Epi& E, int tid_in) {
;     ...
;             PG8_LDB(B0, 1, 0); PG8_LDB(B1, 1, 1); PG8_SCHED; PG8_LDA(At, 1, 0); PG8_STAGE(PG8_SA(0, 1), a2 + hstepA, voffA);
;             PG8_WAIT_V(8); PG8_WAIT_L(0); PG8_BAR; PG8_MMA(0, 0, At, B0); PG8_MMA(0, 1, At, B1); PG8_BAR; PG8_SCHED;
;             PG8_LDA(At, 1, 1); PG8_STAGE(PG8_SB(1, 0), b3, voffB); PG8_STAGE(PG8_SB(1, 1), b3 + hstep, voffB); PG8_STAGE(PG8_SA(1, 0), a3, voffA);
;             PG8_WAIT_V(8); PG8_WAIT_L(0); PG8_BAR; PG8_MMA(1, 0, At, B0); PG8_MMA(1, 1, At, B1); PG8_BAR; PG8_SCHED;
	s_add_i32 s66, 0, 0x18000
	v_add_u32_e32 v157, s66, v151
	s_add_i32 s67, 0, 0x1c000
	ds_read_b128 v[140:143], v157
	ds_read_b128 v[144:147], v157 offset:1024
	ds_read_b128 v[160:163], v157 offset:2048
	ds_read_b128 v[164:167], v157 offset:3072
	v_add_u32_e32 v157, s67, v151
	ds_read_b128 v[168:171], v157
	ds_read_b128 v[172:175], v157 offset:1024
	ds_read_b128 v[176:179], v157 offset:2048
	ds_read_b128 v[180:183], v157 offset:3072
	s_add_u32 s14, s14, 0x40000
	s_addc_u32 s15, s15, 0
	s_mov_b32 m0, s58
	ds_read_b128 v[184:187], v156 offset:32768
	ds_read_b128 v[200:203], v156 offset:33792
	ds_read_b128 v[204:207], v156 offset:34816
	ds_read_b128 v[208:211], v156 offset:35840
	ds_read_b128 v[212:215], v156 offset:36864
	ds_read_b128 v[216:219], v156 offset:37888
	ds_read_b128 v[226:229], v156 offset:38912
	ds_read_b128 v[230:233], v156 offset:39936
	global_load_lds_dwordx4 v134, s[14:15]
	s_mov_b32 m0, s59
	s_nop 0
	global_load_lds_dwordx4 v130, s[14:15]
	s_waitcnt vmcnt(8)
	s_waitcnt lgkmcnt(0)
	s_barrier
	s_setprio 1
	v_mfma_f32_16x16x32_bf16 v[124:127], v[140:143], v[184:187], v[124:127]
	v_mfma_f32_16x16x32_bf16 v[120:123], v[160:163], v[184:187], v[120:123]
	v_mfma_f32_16x16x32_bf16 v[108:111], v[140:143], v[204:207], v[108:111]
	v_mfma_f32_16x16x32_bf16 v[104:107], v[160:163], v[204:207], v[104:107]
	v_mfma_f32_16x16x32_bf16 v[92:95], v[140:143], v[212:215], v[92:95]
	v_mfma_f32_16x16x32_bf16 v[88:91], v[160:163], v[212:215], v[88:91]
	v_mfma_f32_16x16x32_bf16 v[76:79], v[140:143], v[226:229], v[76:79]
	v_mfma_f32_16x16x32_bf16 v[72:75], v[160:163], v[226:229], v[72:75]
	v_mfma_f32_16x16x32_bf16 v[124:127], v[144:147], v[200:203], v[124:127]
	v_mfma_f32_16x16x32_bf16 v[120:123], v[164:167], v[200:203], v[120:123]
	v_mfma_f32_16x16x32_bf16 v[108:111], v[144:147], v[208:211], v[108:111]
	v_mfma_f32_16x16x32_bf16 v[104:107], v[164:167], v[208:211], v[104:107]
	v_mfma_f32_16x16x32_bf16 v[92:95], v[144:147], v[216:219], v[92:95]
	v_mfma_f32_16x16x32_bf16 v[88:91], v[164:167], v[216:219], v[88:91]
	v_mfma_f32_16x16x32_bf16 v[76:79], v[144:147], v[230:233], v[76:79]
	v_mfma_f32_16x16x32_bf16 v[72:75], v[164:167], v[230:233], v[72:75]
	s_setprio 0
	s_setprio 1
	v_mfma_f32_16x16x32_bf16 v[116:119], v[168:171], v[184:187], v[116:119]
	v_mfma_f32_16x16x32_bf16 v[112:115], v[176:179], v[184:187], v[112:115]
	v_mfma_f32_16x16x32_bf16 v[100:103], v[168:171], v[204:207], v[100:103]
	v_mfma_f32_16x16x32_bf16 v[96:99], v[176:179], v[204:207], v[96:99]
	v_mfma_f32_16x16x32_bf16 v[84:87], v[168:171], v[212:215], v[84:87]
	v_mfma_f32_16x16x32_bf16 v[80:83], v[176:179], v[212:215], v[80:83]
	v_mfma_f32_16x16x32_bf16 v[68:71], v[168:171], v[226:229], v[68:71]
	v_mfma_f32_16x16x32_bf16 v[64:67], v[176:179], v[226:229], v[64:67]
	v_mfma_f32_16x16x32_bf16 v[116:119], v[172:175], v[200:203], v[116:119]
	v_mfma_f32_16x16x32_bf16 v[112:115], v[180:183], v[200:203], v[112:115]
	v_mfma_f32_16x16x32_bf16 v[100:103], v[172:175], v[208:211], v[100:103]
	v_mfma_f32_16x16x32_bf16 v[96:99], v[180:183], v[208:211], v[96:99]
	v_mfma_f32_16x16x32_bf16 v[84:87], v[172:175], v[216:219], v[84:87]
	v_mfma_f32_16x16x32_bf16 v[80:83], v[180:183], v[216:219], v[80:83]
	v_mfma_f32_16x16x32_bf16 v[68:71], v[172:175], v[230:233], v[68:71]
	v_mfma_f32_16x16x32_bf16 v[64:67], v[180:183], v[230:233], v[64:67]
	s_setprio 0
	s_barrier
	s_add_i32 s14, s66, s49
	s_mov_b32 m0, s14
	ds_read_b128 v[184:187], v156 offset:49152
	ds_read_b128 v[200:203], v156 offset:50176
	ds_read_b128 v[204:207], v156 offset:51200
	ds_read_b128 v[208:211], v156 offset:52224
	ds_read_b128 v[212:215], v156 offset:53248
	ds_read_b128 v[216:219], v156 offset:54272
	ds_read_b128 v[226:229], v156 offset:55296
	ds_read_b128 v[230:233], v156 offset:56320
	s_add_u32 s12, s12, 0x80
	s_addc_u32 s13, s13, 0
	global_load_lds_dwordx4 v132, s[12:13]
	s_add_i32 m0, s14, 0x2000
	s_nop 0
	global_load_lds_dwordx4 v128, s[12:13]
	s_add_u32 s12, s12, 0x40000
	s_addc_u32 s13, s13, 0
	s_add_i32 s14, s67, s49
	s_mov_b32 m0, s14
	s_nop 0
	global_load_lds_dwordx4 v132, s[12:13]
	s_add_i32 m0, s14, 0x2000
	s_nop 0
	global_load_lds_dwordx4 v128, s[12:13]
	s_mov_b32 m0, s61
	s_nop 0
	s_add_u32 s100, s100, 0x80
	s_addc_u32 s101, s101, 0
	global_load_lds_dwordx4 v134, s[100:101]
	s_mov_b32 m0, s62
	s_nop 0
	global_load_lds_dwordx4 v130, s[100:101]
	s_waitcnt vmcnt(8)
	s_waitcnt lgkmcnt(0)
	s_barrier
	s_setprio 1
	v_mfma_f32_16x16x32_bf16 v[60:63], v[140:143], v[184:187], v[60:63]
	v_mfma_f32_16x16x32_bf16 v[56:59], v[160:163], v[184:187], v[56:59]
	v_mfma_f32_16x16x32_bf16 v[44:47], v[140:143], v[204:207], v[44:47]
	v_mfma_f32_16x16x32_bf16 v[40:43], v[160:163], v[204:207], v[40:43]
	v_mfma_f32_16x16x32_bf16 v[28:31], v[140:143], v[212:215], v[28:31]
	v_mfma_f32_16x16x32_bf16 v[24:27], v[160:163], v[212:215], v[24:27]
	v_mfma_f32_16x16x32_bf16 v[12:15], v[140:143], v[226:229], v[12:15]
	v_mfma_f32_16x16x32_bf16 v[8:11], v[160:163], v[226:229], v[8:11]
	v_mfma_f32_16x16x32_bf16 v[60:63], v[144:147], v[200:203], v[60:63]
	v_mfma_f32_16x16x32_bf16 v[56:59], v[164:167], v[200:203], v[56:59]
	v_mfma_f32_16x16x32_bf16 v[44:47], v[144:147], v[208:211], v[44:47]
	v_mfma_f32_16x16x32_bf16 v[40:43], v[164:167], v[208:211], v[40:43]
	v_mfma_f32_16x16x32_bf16 v[28:31], v[144:147], v[216:219], v[28:31]
	v_mfma_f32_16x16x32_bf16 v[24:27], v[164:167], v[216:219], v[24:27]
	v_mfma_f32_16x16x32_bf16 v[12:15], v[144:147], v[230:233], v[12:15]
	v_mfma_f32_16x16x32_bf16 v[8:11], v[164:167], v[230:233], v[8:11]
	s_setprio 0
	s_setprio 1
	v_mfma_f32_16x16x32_bf16 v[52:55], v[168:171], v[184:187], v[52:55]
	v_mfma_f32_16x16x32_bf16 v[48:51], v[176:179], v[184:187], v[48:51]
	v_mfma_f32_16x16x32_bf16 v[36:39], v[168:171], v[204:207], v[36:39]
	v_mfma_f32_16x16x32_bf16 v[32:35], v[176:179], v[204:207], v[32:35]
	v_mfma_f32_16x16x32_bf16 v[20:23], v[168:171], v[212:215], v[20:23]
	v_mfma_f32_16x16x32_bf16 v[16:19], v[176:179], v[212:215], v[16:19]
	v_mfma_f32_16x16x32_bf16 v[4:7], v[168:171], v[226:229], v[4:7]
	v_mfma_f32_16x16x32_bf16 v[0:3], v[176:179], v[226:229], v[0:3]
	v_mfma_f32_16x16x32_bf16 v[52:55], v[172:175], v[200:203], v[52:55]
	v_mfma_f32_16x16x32_bf16 v[48:51], v[180:183], v[200:203], v[48:51]
	v_mfma_f32_16x16x32_bf16 v[36:39], v[172:175], v[208:211], v[36:39]
	v_mfma_f32_16x16x32_bf16 v[32:35], v[180:183], v[208:211], v[32:35]
	v_mfma_f32_16x16x32_bf16 v[20:23], v[172:175], v[216:219], v[20:23]
	v_mfma_f32_16x16x32_bf16 v[16:19], v[180:183], v[216:219], v[16:19]
	v_mfma_f32_16x16x32_bf16 v[4:7], v[172:175], v[230:233], v[4:7]
	v_mfma_f32_16x16x32_bf16 v[0:3], v[180:183], v[230:233], v[0:3]
	s_setprio 0
	s_barrier
	s_add_i32 s65, s65, 2
	s_add_u32 s51, s51, 0x100
	s_addc_u32 s64, s64, 0
	s_add_u32 s2, s2, 0x100
	s_addc_u32 s3, s3, 0
	s_cmp_gt_u32 s65, 13
	s_cbranch_scc0 .LBB0_526
	s_and_b64 vcc, exec, s[34:35]
	s_cbranch_vccz .LBB0_529
	s_barrier

; #define PG8_STAGE(bufoff, gbase, voff) do { _Pragma("unroll") for (int _i = 0; _i < 2; ++_i) \
;         __builtin_amdgcn_global_load_lds((const unsigned*)((const char*)(gbase) + (voff)[_i]), (PG8_LAS unsigned*)(lds + (bufoff) + ldsw + _i * 8192), 16, 0, 0); } while (0)
; #define PG8_LDA(dst, b, h) do { _Pragma("unroll") for (int m = 0; m < 4; ++m) _Pragma("unroll") for (int k = 0; k < 2; ++k) dst[m][k] = *(const PG8_LAS bf16x8*)(lds + PG8_SA(b, h) + aoff + m * 2048 + k * 1024); } while (0)
; #define PG8_LDB(dst, b, h) do { _Pragma("unroll") for (int n = 0; n < 2; ++n) _Pragma("unroll") for (int k = 0; k < 2; ++k) dst[n][k] = *(const PG8_LAS bf16x8*)(lds + PG8_SB(b, h) + boff + n * 2048 + k * 1024); } while (0)
; #define PG8_MMA(ai, bj, At, Bt) do { __builtin_amdgcn_s_setprio(1); _Pragma("unroll") for (int m = 0; m < 4; ++m) _Pragma("unroll") for (int n = 0; n < 2; ++n) _Pragma("unroll") for (int k = 0; k < 2; ++k) \
;         acc[ai][bj][m][n] = __builtin_amdgcn_mfma_f32_16x16x32_bf16(Bt[n][k], At[m][k], acc[ai][bj][m][n], 0, 0, 0); __builtin_amdgcn_s_setprio(0); } while (0)
; #define PG8_WAIT_V(n) asm volatile("s_waitcnt vmcnt(" #n ")" ::: "memory")
; #define PG8_WAIT_L(n) asm volatile("s_waitcnt lgkmcnt(" #n ")" ::: "memory")
; template <class Epi, class Sched, bool ALIGN_EPI = false, bool SP2 = false>
; __device__ __forceinline__ void gemm_phase(PG8_LAS unsigned char* lds, const Gemm g, const Sched& S, const Epi& E, int tid_in) {
;     ...
;             const bool last = (t == nt - 2);
;             const char* a1 = cA + (size_t)(t + 1) * kstep;
;             const char* a2 = last ? nA : cA + (size_t)(t + 2) * kstep; const char* b2 = last ? nB : cB + (size_t)(t + 2) * kstep;
;             const char* a3 = a2 + kstep; const char* b3 = b2 + kstep;
;             if (last && has_next) S.a_ready(nxt);
;             if constexpr (SP2) {
;             PG8_LDB(B0, 0, 0); PG8_LDB(B1, 0, 1); PG8_SCHED; PG8_LDA(At, 0, 0); PG8_STAGE(PG8_SA(1, 1), a1 + hstepA, voffA);
;             PG8_WAIT_V(8); PG8_WAIT_L(0); PG8_BAR; PG8_MMA(0, 0, At, B0); PG8_MMA(0, 1, At, B1); PG8_BAR; PG8_SCHED;
;             PG8_LDA(At, 0, 1); PG8_STAGE(PG8_SB(0, 0), b2, voffB); PG8_STAGE(PG8_SB(0, 1), b2 + hstep, voffB); PG8_STAGE(PG8_SA(0, 0), a2, voffA);
;             PG8_WAIT_V(8); PG8_WAIT_L(0); PG8_BAR; PG8_MMA(1, 0, At, B0); PG8_MMA(1, 1, At, B1); PG8_BAR; PG8_SCHED;
.LBB0_691:
	s_add_u32 s28, s26, 0xfffc0080
	s_addc_u32 s29, s27, -1
	s_add_i32 s57, 0, 0x10000
	s_cmp_eq_u32 s56, 12
	s_cselect_b32 s31, s15, s29
	s_cselect_b32 s30, s52, s28
	v_add_u32_e32 v147, s57, v145
	s_cselect_b32 s29, s13, s55
	s_cselect_b32 s28, s53, s54
	s_add_i32 s60, 0, 0x14000
	ds_read_b128 v[140:143], v147
	ds_read_b128 v[148:151], v147 offset:1024
	ds_read_b128 v[152:155], v147 offset:2048
	ds_read_b128 v[156:159], v147 offset:3072
	v_add_u32_e32 v147, s60, v145
	ds_read_b128 v[160:163], v147
	ds_read_b128 v[164:167], v147 offset:1024
	ds_read_b128 v[168:171], v147 offset:2048
	ds_read_b128 v[172:175], v147 offset:3072
	s_add_i32 m0, s42, 0xc000
	ds_read_b128 v[176:179], v146
	ds_read_b128 v[180:183], v146 offset:1024
	ds_read_b128 v[184:187], v146 offset:2048
	ds_read_b128 v[200:203], v146 offset:3072
	ds_read_b128 v[204:207], v146 offset:4096
	ds_read_b128 v[208:211], v146 offset:5120
	ds_read_b128 v[212:215], v146 offset:6144
	ds_read_b128 v[216:219], v146 offset:7168
	global_load_lds_dwordx4 v138, s[26:27]
	s_add_i32 m0, s42, 0xe000
	s_nop 0
	global_load_lds_dwordx4 v136, s[26:27]
	s_waitcnt vmcnt(8)
	s_waitcnt lgkmcnt(0)
	s_barrier
	s_setprio 1
	v_mfma_f32_16x16x32_bf16 v[124:127], v[140:143], v[176:179], v[124:127]
	v_mfma_f32_16x16x32_bf16 v[120:123], v[152:155], v[176:179], v[120:123]
	v_mfma_f32_16x16x32_bf16 v[108:111], v[140:143], v[184:187], v[108:111]
	v_mfma_f32_16x16x32_bf16 v[104:107], v[152:155], v[184:187], v[104:107]
	v_mfma_f32_16x16x32_bf16 v[92:95], v[140:143], v[204:207], v[92:95]
	v_mfma_f32_16x16x32_bf16 v[88:91], v[152:155], v[204:207], v[88:91]
	v_mfma_f32_16x16x32_bf16 v[76:79], v[140:143], v[212:215], v[76:79]
	v_mfma_f32_16x16x32_bf16 v[72:75], v[152:155], v[212:215], v[72:75]
	v_mfma_f32_16x16x32_bf16 v[124:127], v[148:151], v[180:183], v[124:127]
	v_mfma_f32_16x16x32_bf16 v[120:123], v[156:159], v[180:183], v[120:123]
	v_mfma_f32_16x16x32_bf16 v[108:111], v[148:151], v[200:203], v[108:111]
	v_mfma_f32_16x16x32_bf16 v[104:107], v[156:159], v[200:203], v[104:107]
	v_mfma_f32_16x16x32_bf16 v[92:95], v[148:151], v[208:211], v[92:95]
	v_mfma_f32_16x16x32_bf16 v[88:91], v[156:159], v[208:211], v[88:91]
	v_mfma_f32_16x16x32_bf16 v[76:79], v[148:151], v[216:219], v[76:79]
	v_mfma_f32_16x16x32_bf16 v[72:75], v[156:159], v[216:219], v[72:75]
	s_setprio 0
	s_setprio 1
	v_mfma_f32_16x16x32_bf16 v[116:119], v[160:163], v[176:179], v[116:119]
	v_mfma_f32_16x16x32_bf16 v[112:115], v[168:171], v[176:179], v[112:115]
	v_mfma_f32_16x16x32_bf16 v[100:103], v[160:163], v[184:187], v[100:103]
	v_mfma_f32_16x16x32_bf16 v[96:99], v[168:171], v[184:187], v[96:99]
	v_mfma_f32_16x16x32_bf16 v[84:87], v[160:163], v[204:207], v[84:87]
	v_mfma_f32_16x16x32_bf16 v[80:83], v[168:171], v[204:207], v[80:83]
	v_mfma_f32_16x16x32_bf16 v[68:71], v[160:163], v[212:215], v[68:71]
	v_mfma_f32_16x16x32_bf16 v[64:67], v[168:171], v[212:215], v[64:67]
	v_mfma_f32_16x16x32_bf16 v[116:119], v[164:167], v[180:183], v[116:119]
	v_mfma_f32_16x16x32_bf16 v[112:115], v[172:175], v[180:183], v[112:115]
	v_mfma_f32_16x16x32_bf16 v[100:103], v[164:167], v[200:203], v[100:103]
	v_mfma_f32_16x16x32_bf16 v[96:99], v[172:175], v[200:203], v[96:99]
	v_mfma_f32_16x16x32_bf16 v[84:87], v[164:167], v[208:211], v[84:87]
	v_mfma_f32_16x16x32_bf16 v[80:83], v[172:175], v[208:211], v[80:83]
	v_mfma_f32_16x16x32_bf16 v[68:71], v[164:167], v[216:219], v[68:71]
	v_mfma_f32_16x16x32_bf16 v[64:67], v[172:175], v[216:219], v[64:67]
	s_setprio 0
	s_barrier
	s_add_i32 s57, s57, s41
	s_mov_b32 m0, s57
	ds_read_b128 v[176:179], v146 offset:16384
	ds_read_b128 v[180:183], v146 offset:17408
	ds_read_b128 v[184:187], v146 offset:18432
	ds_read_b128 v[200:203], v146 offset:19456
	ds_read_b128 v[204:207], v146 offset:20480
	ds_read_b128 v[208:211], v146 offset:21504
	ds_read_b128 v[212:215], v146 offset:22528
	ds_read_b128 v[216:219], v146 offset:23552
	global_load_lds_dwordx4 v132, s[28:29]
	s_add_i32 m0, s57, 0x2000
	s_add_u32 s58, s28, 0x40000
	s_addc_u32 s59, s29, 0
	s_add_i32 s57, s60, s41
	global_load_lds_dwordx4 v128, s[28:29]
	s_mov_b32 m0, s57
	s_mov_b64 s[100:101], s[30:31]
	global_load_lds_dwordx4 v132, s[58:59]
	s_add_i32 m0, s57, 0x2000
	s_nop 0
	global_load_lds_dwordx4 v128, s[58:59]
	s_mov_b32 m0, s42
	s_nop 0
	global_load_lds_dwordx4 v134, s[100:101]
	s_mov_b32 m0, s43
	s_nop 0
	global_load_lds_dwordx4 v130, s[100:101]
	s_waitcnt vmcnt(8)
	s_waitcnt lgkmcnt(0)
	s_barrier
	s_setprio 1
	v_mfma_f32_16x16x32_bf16 v[60:63], v[140:143], v[176:179], v[60:63]
	v_mfma_f32_16x16x32_bf16 v[56:59], v[152:155], v[176:179], v[56:59]
	v_mfma_f32_16x16x32_bf16 v[44:47], v[140:143], v[184:187], v[44:47]
	v_mfma_f32_16x16x32_bf16 v[40:43], v[152:155], v[184:187], v[40:43]
	v_mfma_f32_16x16x32_bf16 v[28:31], v[140:143], v[204:207], v[28:31]
	v_mfma_f32_16x16x32_bf16 v[24:27], v[152:155], v[204:207], v[24:27]
	v_mfma_f32_16x16x32_bf16 v[12:15], v[140:143], v[212:215], v[12:15]
	v_mfma_f32_16x16x32_bf16 v[8:11], v[152:155], v[212:215], v[8:11]
	v_mfma_f32_16x16x32_bf16 v[60:63], v[148:151], v[180:183], v[60:63]
	v_mfma_f32_16x16x32_bf16 v[56:59], v[156:159], v[180:183], v[56:59]
	v_mfma_f32_16x16x32_bf16 v[44:47], v[148:151], v[200:203], v[44:47]
	v_mfma_f32_16x16x32_bf16 v[40:43], v[156:159], v[200:203], v[40:43]
	v_mfma_f32_16x16x32_bf16 v[28:31], v[148:151], v[208:211], v[28:31]
	v_mfma_f32_16x16x32_bf16 v[24:27], v[156:159], v[208:211], v[24:27]
	v_mfma_f32_16x16x32_bf16 v[12:15], v[148:151], v[216:219], v[12:15]
	v_mfma_f32_16x16x32_bf16 v[8:11], v[156:159], v[216:219], v[8:11]
	s_setprio 0
	s_setprio 1
	v_mfma_f32_16x16x32_bf16 v[52:55], v[160:163], v[176:179], v[52:55]
	v_mfma_f32_16x16x32_bf16 v[48:51], v[168:171], v[176:179], v[48:51]
	v_mfma_f32_16x16x32_bf16 v[36:39], v[160:163], v[184:187], v[36:39]
	v_mfma_f32_16x16x32_bf16 v[32:35], v[168:171], v[184:187], v[32:35]
	v_mfma_f32_16x16x32_bf16 v[20:23], v[160:163], v[204:207], v[20:23]
	v_mfma_f32_16x16x32_bf16 v[16:19], v[168:171], v[204:207], v[16:19]
	v_mfma_f32_16x16x32_bf16 v[4:7], v[160:163], v[212:215], v[4:7]
	v_mfma_f32_16x16x32_bf16 v[0:3], v[168:171], v[212:215], v[0:3]
	v_mfma_f32_16x16x32_bf16 v[52:55], v[164:167], v[180:183], v[52:55]
	v_mfma_f32_16x16x32_bf16 v[48:51], v[172:175], v[180:183], v[48:51]
	v_mfma_f32_16x16x32_bf16 v[36:39], v[164:167], v[200:203], v[36:39]
	v_mfma_f32_16x16x32_bf16 v[32:35], v[172:175], v[200:203], v[32:35]
	v_mfma_f32_16x16x32_bf16 v[20:23], v[164:167], v[208:211], v[20:23]
	v_mfma_f32_16x16x32_bf16 v[16:19], v[172:175], v[208:211], v[16:19]
	v_mfma_f32_16x16x32_bf16 v[4:7], v[164:167], v[216:219], v[4:7]
	v_mfma_f32_16x16x32_bf16 v[0:3], v[172:175], v[216:219], v[0:3]
	s_setprio 0
	s_barrier
; #define PG8_STAGE(bufoff, gbase, voff) do { _Pragma("unroll") for (int _i = 0; _i < 2; ++_i) \
;         __builtin_amdgcn_global_load_lds((const unsigned*)((const char*)(gbase) + (voff)[_i]), (PG8_LAS unsigned*)(lds + (bufoff) + ldsw + _i * 8192), 16, 0, 0); } while (0)
; #define PG8_LDA(dst, b, h) do { _Pragma("unroll") for (int m = 0; m < 4; ++m) _Pragma("unroll") for (int k = 0; k < 2; ++k) dst[m][k] = *(const PG8_LAS bf16x8*)(lds + PG8_SA(b, h) + aoff + m * 2048 + k * 1024); } while (0)
; #define PG8_LDB(dst, b, h) do { _Pragma("unroll") for (int n = 0; n < 2; ++n) _Pragma("unroll") for (int k = 0; k < 2; ++k) dst[n][k] = *(const PG8_LAS bf16x8*)(lds + PG8_SB(b, h) + boff + n * 2048 + k * 1024); } while (0)
; #define PG8_MMA(ai, bj, At, Bt) do { __builtin_amdgcn_s_setprio(1); _Pragma("unroll") for (int m = 0; m < 4; ++m) _Pragma("unroll") for (int n = 0; n < 2; ++n) _Pragma("unroll") for (int k = 0; k < 2; ++k) \
;         acc[ai][bj][m][n] = __builtin_amdgcn_mfma_f32_16x16x32_bf16(Bt[n][k], At[m][k], acc[ai][bj][m][n], 0, 0, 0); __builtin_amdgcn_s_setprio(0); } while (0)
; #define PG8_WAIT_V(n) asm volatile("s_waitcnt vmcnt(" #n ")" ::: "memory")
; #define PG8_WAIT_L(n) asm volatile("s_waitcnt lgkmcnt(" #n ")" ::: "memory")
; #define PG8_BAR __builtin_amdgcn_s_barrier()
; #define PG8_SCHED __builtin_amdgcn_sched_barrier(0)
; template <class Epi, class Sched, bool ALIGN_EPI = false, bool SP2 = false>
; __device__ __forceinline__ void gemm_phase(PG8_LAS unsigned char* lds, const Gemm g, const Sched& S, const Epi& E, int tid_in) {
;     ...
;             PG8_LDB(B0, 1, 0); PG8_LDB(B1, 1, 1); PG8_SCHED; PG8_LDA(At, 1, 0); PG8_STAGE(PG8_SA(0, 1), a2 + hstepA, voffA);
;             PG8_WAIT_V(8); PG8_WAIT_L(0); PG8_BAR; PG8_MMA(0, 0, At, B0); PG8_MMA(0, 1, At, B1); PG8_BAR; PG8_SCHED;
;             PG8_LDA(At, 1, 1); PG8_STAGE(PG8_SB(1, 0), b3, voffB); PG8_STAGE(PG8_SB(1, 1), b3 + hstep, voffB); PG8_STAGE(PG8_SA(1, 0), a3, voffA);
;             PG8_WAIT_V(8); PG8_WAIT_L(0); PG8_BAR; PG8_MMA(1, 0, At, B0); PG8_MMA(1, 1, At, B1); PG8_BAR; PG8_SCHED;
	s_add_i32 s57, 0, 0x18000
	v_add_u32_e32 v147, s57, v145
	s_add_i32 s58, 0, 0x1c000
	ds_read_b128 v[140:143], v147
	ds_read_b128 v[148:151], v147 offset:1024
	ds_read_b128 v[152:155], v147 offset:2048
	ds_read_b128 v[156:159], v147 offset:3072
	v_add_u32_e32 v147, s58, v145
	ds_read_b128 v[160:163], v147
	ds_read_b128 v[164:167], v147 offset:1024
	ds_read_b128 v[168:171], v147 offset:2048
	ds_read_b128 v[172:175], v147 offset:3072
	s_add_u32 s30, s30, 0x40000
	s_addc_u32 s31, s31, 0
	s_mov_b32 m0, s44
	ds_read_b128 v[176:179], v146 offset:32768
	ds_read_b128 v[180:183], v146 offset:33792
	ds_read_b128 v[184:187], v146 offset:34816
	ds_read_b128 v[200:203], v146 offset:35840
	ds_read_b128 v[204:207], v146 offset:36864
	ds_read_b128 v[208:211], v146 offset:37888
	ds_read_b128 v[212:215], v146 offset:38912
	ds_read_b128 v[216:219], v146 offset:39936
	global_load_lds_dwordx4 v134, s[30:31]
	s_mov_b32 m0, s45
	s_nop 0
	global_load_lds_dwordx4 v130, s[30:31]
	s_waitcnt vmcnt(8)
	s_waitcnt lgkmcnt(0)
	s_barrier
	s_setprio 1
	v_mfma_f32_16x16x32_bf16 v[124:127], v[140:143], v[176:179], v[124:127]
	v_mfma_f32_16x16x32_bf16 v[120:123], v[152:155], v[176:179], v[120:123]
	v_mfma_f32_16x16x32_bf16 v[108:111], v[140:143], v[184:187], v[108:111]
	v_mfma_f32_16x16x32_bf16 v[104:107], v[152:155], v[184:187], v[104:107]
	v_mfma_f32_16x16x32_bf16 v[92:95], v[140:143], v[204:207], v[92:95]
	v_mfma_f32_16x16x32_bf16 v[88:91], v[152:155], v[204:207], v[88:91]
	v_mfma_f32_16x16x32_bf16 v[76:79], v[140:143], v[212:215], v[76:79]
	v_mfma_f32_16x16x32_bf16 v[72:75], v[152:155], v[212:215], v[72:75]
	v_mfma_f32_16x16x32_bf16 v[124:127], v[148:151], v[180:183], v[124:127]
	v_mfma_f32_16x16x32_bf16 v[120:123], v[156:159], v[180:183], v[120:123]
	v_mfma_f32_16x16x32_bf16 v[108:111], v[148:151], v[200:203], v[108:111]
	v_mfma_f32_16x16x32_bf16 v[104:107], v[156:159], v[200:203], v[104:107]
	v_mfma_f32_16x16x32_bf16 v[92:95], v[148:151], v[208:211], v[92:95]
	v_mfma_f32_16x16x32_bf16 v[88:91], v[156:159], v[208:211], v[88:91]
	v_mfma_f32_16x16x32_bf16 v[76:79], v[148:151], v[216:219], v[76:79]
	v_mfma_f32_16x16x32_bf16 v[72:75], v[156:159], v[216:219], v[72:75]
	s_setprio 0
	s_setprio 1
	v_mfma_f32_16x16x32_bf16 v[116:119], v[160:163], v[176:179], v[116:119]
	v_mfma_f32_16x16x32_bf16 v[112:115], v[168:171], v[176:179], v[112:115]
	v_mfma_f32_16x16x32_bf16 v[100:103], v[160:163], v[184:187], v[100:103]
	v_mfma_f32_16x16x32_bf16 v[96:99], v[168:171], v[184:187], v[96:99]
	v_mfma_f32_16x16x32_bf16 v[84:87], v[160:163], v[204:207], v[84:87]
	v_mfma_f32_16x16x32_bf16 v[80:83], v[168:171], v[204:207], v[80:83]
	v_mfma_f32_16x16x32_bf16 v[68:71], v[160:163], v[212:215], v[68:71]
	v_mfma_f32_16x16x32_bf16 v[64:67], v[168:171], v[212:215], v[64:67]
	v_mfma_f32_16x16x32_bf16 v[116:119], v[164:167], v[180:183], v[116:119]
	v_mfma_f32_16x16x32_bf16 v[112:115], v[172:175], v[180:183], v[112:115]
	v_mfma_f32_16x16x32_bf16 v[100:103], v[164:167], v[200:203], v[100:103]
	v_mfma_f32_16x16x32_bf16 v[96:99], v[172:175], v[200:203], v[96:99]
	v_mfma_f32_16x16x32_bf16 v[84:87], v[164:167], v[208:211], v[84:87]
	v_mfma_f32_16x16x32_bf16 v[80:83], v[172:175], v[208:211], v[80:83]
	v_mfma_f32_16x16x32_bf16 v[68:71], v[164:167], v[216:219], v[68:71]
	v_mfma_f32_16x16x32_bf16 v[64:67], v[172:175], v[216:219], v[64:67]
	s_setprio 0
	s_barrier
	s_add_i32 s30, s57, s41
	s_mov_b32 m0, s30
	ds_read_b128 v[176:179], v146 offset:49152
	ds_read_b128 v[180:183], v146 offset:50176
	ds_read_b128 v[184:187], v146 offset:51200
	ds_read_b128 v[200:203], v146 offset:52224
	ds_read_b128 v[204:207], v146 offset:53248
	ds_read_b128 v[208:211], v146 offset:54272
	ds_read_b128 v[212:215], v146 offset:55296
	ds_read_b128 v[216:219], v146 offset:56320
	s_add_u32 s28, s28, 0x80
	s_addc_u32 s29, s29, 0
	global_load_lds_dwordx4 v132, s[28:29]
	s_add_i32 m0, s30, 0x2000
	s_nop 0
	global_load_lds_dwordx4 v128, s[28:29]
	s_add_u32 s28, s28, 0x40000
	s_addc_u32 s29, s29, 0
	s_add_i32 s30, s58, s41
	s_mov_b32 m0, s30
	s_nop 0
	global_load_lds_dwordx4 v132, s[28:29]
	s_add_i32 m0, s30, 0x2000
	s_nop 0
	global_load_lds_dwordx4 v128, s[28:29]
	s_mov_b32 m0, s46
	s_nop 0
	s_add_u32 s100, s100, 0x80
	s_addc_u32 s101, s101, 0
	global_load_lds_dwordx4 v134, s[100:101]
	s_mov_b32 m0, s47
	s_nop 0
	global_load_lds_dwordx4 v130, s[100:101]
	s_waitcnt vmcnt(8)
	s_waitcnt lgkmcnt(0)
	s_barrier
	s_setprio 1
	v_mfma_f32_16x16x32_bf16 v[60:63], v[140:143], v[176:179], v[60:63]
	v_mfma_f32_16x16x32_bf16 v[56:59], v[152:155], v[176:179], v[56:59]
	v_mfma_f32_16x16x32_bf16 v[44:47], v[140:143], v[184:187], v[44:47]
	v_mfma_f32_16x16x32_bf16 v[40:43], v[152:155], v[184:187], v[40:43]
	v_mfma_f32_16x16x32_bf16 v[28:31], v[140:143], v[204:207], v[28:31]
	v_mfma_f32_16x16x32_bf16 v[24:27], v[152:155], v[204:207], v[24:27]
	v_mfma_f32_16x16x32_bf16 v[12:15], v[140:143], v[212:215], v[12:15]
	v_mfma_f32_16x16x32_bf16 v[8:11], v[152:155], v[212:215], v[8:11]
	v_mfma_f32_16x16x32_bf16 v[60:63], v[148:151], v[180:183], v[60:63]
	v_mfma_f32_16x16x32_bf16 v[56:59], v[156:159], v[180:183], v[56:59]
	v_mfma_f32_16x16x32_bf16 v[44:47], v[148:151], v[200:203], v[44:47]
	v_mfma_f32_16x16x32_bf16 v[40:43], v[156:159], v[200:203], v[40:43]
	v_mfma_f32_16x16x32_bf16 v[28:31], v[148:151], v[208:211], v[28:31]
	v_mfma_f32_16x16x32_bf16 v[24:27], v[156:159], v[208:211], v[24:27]
	v_mfma_f32_16x16x32_bf16 v[12:15], v[148:151], v[216:219], v[12:15]
	v_mfma_f32_16x16x32_bf16 v[8:11], v[156:159], v[216:219], v[8:11]
	s_setprio 0
	s_setprio 1
	v_mfma_f32_16x16x32_bf16 v[52:55], v[160:163], v[176:179], v[52:55]
	v_mfma_f32_16x16x32_bf16 v[48:51], v[168:171], v[176:179], v[48:51]
	v_mfma_f32_16x16x32_bf16 v[36:39], v[160:163], v[184:187], v[36:39]
	v_mfma_f32_16x16x32_bf16 v[32:35], v[168:171], v[184:187], v[32:35]
	v_mfma_f32_16x16x32_bf16 v[20:23], v[160:163], v[204:207], v[20:23]
	v_mfma_f32_16x16x32_bf16 v[16:19], v[168:171], v[204:207], v[16:19]
	v_mfma_f32_16x16x32_bf16 v[4:7], v[160:163], v[212:215], v[4:7]
	v_mfma_f32_16x16x32_bf16 v[0:3], v[168:171], v[212:215], v[0:3]
	v_mfma_f32_16x16x32_bf16 v[52:55], v[164:167], v[180:183], v[52:55]
	v_mfma_f32_16x16x32_bf16 v[48:51], v[172:175], v[180:183], v[48:51]
	v_mfma_f32_16x16x32_bf16 v[36:39], v[164:167], v[200:203], v[36:39]
	v_mfma_f32_16x16x32_bf16 v[32:35], v[172:175], v[200:203], v[32:35]
	v_mfma_f32_16x16x32_bf16 v[20:23], v[164:167], v[208:211], v[20:23]
	v_mfma_f32_16x16x32_bf16 v[16:19], v[172:175], v[208:211], v[16:19]
	v_mfma_f32_16x16x32_bf16 v[4:7], v[164:167], v[216:219], v[4:7]
	v_mfma_f32_16x16x32_bf16 v[0:3], v[172:175], v[216:219], v[0:3]
	s_setprio 0
	s_barrier
	s_add_i32 s56, s56, 2
	s_add_u32 s54, s54, 0x100
	s_addc_u32 s55, s55, 0
	s_add_u32 s26, s26, 0x100
	s_addc_u32 s27, s27, 0
	s_cmp_gt_u32 s56, 13
	s_cbranch_scc0 .LBB0_691
	v_readlane_b32 s56, v255, 17
	s_and_b64 vcc, exec, s[10:11]
	s_mov_b64 s[30:31], 0x10000600
	v_readlane_b32 s57, v255, 18
	v_readlane_b32 s58, v255, 19
	v_readlane_b32 s59, v255, 20
	s_cbranch_vccz .LBB0_694
	s_barrier

; #define PG8_STAGE(bufoff, gbase, voff) do { _Pragma("unroll") for (int _i = 0; _i < 2; ++_i) \
;         __builtin_amdgcn_global_load_lds((const unsigned*)((const char*)(gbase) + (voff)[_i]), (PG8_LAS unsigned*)(lds + (bufoff) + ldsw + _i * 8192), 16, 0, 0); } while (0)
; #define PG8_LDA(dst, b, h) do { _Pragma("unroll") for (int m = 0; m < 4; ++m) _Pragma("unroll") for (int k = 0; k < 2; ++k) dst[m][k] = *(const PG8_LAS bf16x8*)(lds + PG8_SA(b, h) + aoff + m * 2048 + k * 1024); } while (0)
; #define PG8_LDB(dst, b, h) do { _Pragma("unroll") for (int n = 0; n < 2; ++n) _Pragma("unroll") for (int k = 0; k < 2; ++k) dst[n][k] = *(const PG8_LAS bf16x8*)(lds + PG8_SB(b, h) + boff + n * 2048 + k * 1024); } while (0)
; #define PG8_MMA(ai, bj, At, Bt) do { __builtin_amdgcn_s_setprio(1); _Pragma("unroll") for (int m = 0; m < 4; ++m) _Pragma("unroll") for (int n = 0; n < 2; ++n) _Pragma("unroll") for (int k = 0; k < 2; ++k) \
;         acc[ai][bj][m][n] = __builtin_amdgcn_mfma_f32_16x16x32_bf16(Bt[n][k], At[m][k], acc[ai][bj][m][n], 0, 0, 0); __builtin_amdgcn_s_setprio(0); } while (0)
; #define PG8_WAIT_V(n) asm volatile("s_waitcnt vmcnt(" #n ")" ::: "memory")
; #define PG8_WAIT_L(n) asm volatile("s_waitcnt lgkmcnt(" #n ")" ::: "memory")
; #define PG8_BAR __builtin_amdgcn_s_barrier()
; #define PG8_SCHED __builtin_amdgcn_sched_barrier(0)
; template <class Epi, class Sched, bool ALIGN_EPI = false, bool SP2 = false>
; __device__ __forceinline__ void gemm_phase(PG8_LAS unsigned char* lds, const Gemm g, const Sched& S, const Epi& E, int tid_in) {
;     ...
;             const bool last = (t == nt - 2);
;             const char* a1 = cA + (size_t)(t + 1) * kstep;
;             const char* a2 = last ? nA : cA + (size_t)(t + 2) * kstep; const char* b2 = last ? nB : cB + (size_t)(t + 2) * kstep;
;             const char* a3 = a2 + kstep; const char* b3 = b2 + kstep;
;             if (last && has_next) S.a_ready(nxt);
;             if constexpr (SP2) {
;             PG8_LDB(B0, 0, 0); PG8_LDB(B1, 0, 1); PG8_SCHED; PG8_LDA(At, 0, 0); PG8_STAGE(PG8_SA(1, 1), a1 + hstepA, voffA);
;             PG8_WAIT_V(8); PG8_WAIT_L(0); PG8_BAR; PG8_MMA(0, 0, At, B0); PG8_MMA(0, 1, At, B1); PG8_BAR; PG8_SCHED;
;             PG8_LDA(At, 0, 1); PG8_STAGE(PG8_SB(0, 0), b2, voffB); PG8_STAGE(PG8_SB(0, 1), b2 + hstep, voffB); PG8_STAGE(PG8_SA(0, 0), a2, voffA);
.LBB0_782:
	s_add_u32 s26, s24, 0xfffc0080
	s_addc_u32 s27, s25, -1
	s_add_i32 s54, 0, 0x10000
	s_cmp_eq_u32 s53, 28
	s_cselect_b32 s29, s15, s27
	s_cselect_b32 s28, s49, s26
	s_cselect_b32 s27, s13, s52
	s_cselect_b32 s26, s50, s51
	s_add_i32 s56, 0, 0x14000
	v_add_u32_e32 v158, s54, v156
	v_add_u32_e32 v174, s56, v156
	ds_read_b128 v[96:99], v158
	ds_read_b128 v[100:103], v158 offset:1024
	ds_read_b128 v[150:153], v158 offset:2048
	ds_read_b128 v[158:161], v158 offset:3072
	ds_read_b128 v[162:165], v174
	ds_read_b128 v[166:169], v174 offset:1024
	ds_read_b128 v[170:173], v174 offset:2048
	ds_read_b128 v[174:177], v174 offset:3072
	s_add_i32 m0, s38, 0xc000
	ds_read_b128 v[178:181], v157
	ds_read_b128 v[182:185], v157 offset:1024
	ds_read_b128 v[186:189], v157 offset:2048
	ds_read_b128 v[200:203], v157 offset:3072
	ds_read_b128 v[204:207], v157 offset:4096
	ds_read_b128 v[208:211], v157 offset:5120
	ds_read_b128 v[212:215], v157 offset:6144
	ds_read_b128 v[216:219], v157 offset:7168
	global_load_lds_dwordx4 v148, s[24:25]
	s_add_i32 m0, s38, 0xe000
	s_nop 0
	global_load_lds_dwordx4 v146, s[24:25]
	s_waitcnt vmcnt(8)
	s_waitcnt lgkmcnt(0)
	s_barrier
	s_setprio 1
	v_mfma_f32_16x16x32_bf16 v[132:135], v[96:99], v[178:181], v[132:135]
	v_mfma_f32_16x16x32_bf16 v[128:131], v[150:153], v[178:181], v[128:131]
	v_mfma_f32_16x16x32_bf16 v[124:127], v[96:99], v[186:189], v[124:127]
	v_mfma_f32_16x16x32_bf16 v[120:123], v[150:153], v[186:189], v[120:123]
	v_mfma_f32_16x16x32_bf16 v[116:119], v[96:99], v[204:207], v[116:119]
	v_mfma_f32_16x16x32_bf16 v[112:115], v[150:153], v[204:207], v[112:115]
	v_mfma_f32_16x16x32_bf16 v[108:111], v[96:99], v[212:215], v[108:111]
	v_mfma_f32_16x16x32_bf16 v[104:107], v[150:153], v[212:215], v[104:107]
	v_mfma_f32_16x16x32_bf16 v[132:135], v[100:103], v[182:185], v[132:135]
	v_mfma_f32_16x16x32_bf16 v[128:131], v[158:161], v[182:185], v[128:131]
	v_mfma_f32_16x16x32_bf16 v[124:127], v[100:103], v[200:203], v[124:127]
	v_mfma_f32_16x16x32_bf16 v[120:123], v[158:161], v[200:203], v[120:123]
	v_mfma_f32_16x16x32_bf16 v[116:119], v[100:103], v[208:211], v[116:119]
	v_mfma_f32_16x16x32_bf16 v[112:115], v[158:161], v[208:211], v[112:115]
	v_mfma_f32_16x16x32_bf16 v[108:111], v[100:103], v[216:219], v[108:111]
	v_mfma_f32_16x16x32_bf16 v[104:107], v[158:161], v[216:219], v[104:107]
	s_setprio 0
	s_setprio 1
	v_mfma_f32_16x16x32_bf16 v[60:63], v[162:165], v[178:181], v[60:63]
	v_mfma_f32_16x16x32_bf16 v[56:59], v[170:173], v[178:181], v[56:59]
	v_mfma_f32_16x16x32_bf16 v[52:55], v[162:165], v[186:189], v[52:55]
	v_mfma_f32_16x16x32_bf16 v[48:51], v[170:173], v[186:189], v[48:51]
	v_mfma_f32_16x16x32_bf16 v[44:47], v[162:165], v[204:207], v[44:47]
	v_mfma_f32_16x16x32_bf16 v[40:43], v[170:173], v[204:207], v[40:43]
	v_mfma_f32_16x16x32_bf16 v[36:39], v[162:165], v[212:215], v[36:39]
	v_mfma_f32_16x16x32_bf16 v[32:35], v[170:173], v[212:215], v[32:35]
	v_mfma_f32_16x16x32_bf16 v[60:63], v[166:169], v[182:185], v[60:63]
	v_mfma_f32_16x16x32_bf16 v[56:59], v[174:177], v[182:185], v[56:59]
	v_mfma_f32_16x16x32_bf16 v[52:55], v[166:169], v[200:203], v[52:55]
	v_mfma_f32_16x16x32_bf16 v[48:51], v[174:177], v[200:203], v[48:51]
	v_mfma_f32_16x16x32_bf16 v[44:47], v[166:169], v[208:211], v[44:47]
	v_mfma_f32_16x16x32_bf16 v[40:43], v[174:177], v[208:211], v[40:43]
	v_mfma_f32_16x16x32_bf16 v[36:39], v[166:169], v[216:219], v[36:39]
	v_mfma_f32_16x16x32_bf16 v[32:35], v[174:177], v[216:219], v[32:35]
	s_setprio 0
	s_barrier
	s_add_i32 s54, s54, s35
	s_mov_b64 s[100:101], s[26:27]
	s_mov_b32 m0, s54
	ds_read_b128 v[178:181], v157 offset:16384
	ds_read_b128 v[182:185], v157 offset:17408
	ds_read_b128 v[186:189], v157 offset:18432
	ds_read_b128 v[200:203], v157 offset:19456
	ds_read_b128 v[204:207], v157 offset:20480
	ds_read_b128 v[208:211], v157 offset:21504
	ds_read_b128 v[212:215], v157 offset:22528
	ds_read_b128 v[216:219], v157 offset:23552
	global_load_lds_dwordx4 v190, s[100:101]
	s_add_i32 m0, s54, 0x2000
	s_add_u32 s54, s26, 0x80000
	s_addc_u32 s55, s27, 0
	s_add_i32 s56, s56, s35
	global_load_lds_dwordx4 v136, s[100:101]
	s_mov_b32 m0, s56
	v_lshl_add_u64 v[232:233], s[28:29], 0, v[138:139]
	global_load_lds_dwordx4 v190, s[54:55]
	s_add_i32 m0, s56, 0x2000
	s_nop 0
	global_load_lds_dwordx4 v136, s[54:55]
	v_lshl_add_u64 v[230:231], s[28:29], 0, v[140:141]
	s_mov_b32 m0, s38
	s_nop 0
	global_load_lds_dwordx4 v[230:231], off
	s_mov_b32 m0, s40
	s_nop 0
	global_load_lds_dwordx4 v[232:233], off
	s_waitcnt vmcnt(8)
	s_waitcnt lgkmcnt(0)
	s_barrier
; #define PG8_STAGE(bufoff, gbase, voff) do { _Pragma("unroll") for (int _i = 0; _i < 2; ++_i) \
;         __builtin_amdgcn_global_load_lds((const unsigned*)((const char*)(gbase) + (voff)[_i]), (PG8_LAS unsigned*)(lds + (bufoff) + ldsw + _i * 8192), 16, 0, 0); } while (0)
; #define PG8_LDA(dst, b, h) do { _Pragma("unroll") for (int m = 0; m < 4; ++m) _Pragma("unroll") for (int k = 0; k < 2; ++k) dst[m][k] = *(const PG8_LAS bf16x8*)(lds + PG8_SA(b, h) + aoff + m * 2048 + k * 1024); } while (0)
; #define PG8_LDB(dst, b, h) do { _Pragma("unroll") for (int n = 0; n < 2; ++n) _Pragma("unroll") for (int k = 0; k < 2; ++k) dst[n][k] = *(const PG8_LAS bf16x8*)(lds + PG8_SB(b, h) + boff + n * 2048 + k * 1024); } while (0)
; #define PG8_MMA(ai, bj, At, Bt) do { __builtin_amdgcn_s_setprio(1); _Pragma("unroll") for (int m = 0; m < 4; ++m) _Pragma("unroll") for (int n = 0; n < 2; ++n) _Pragma("unroll") for (int k = 0; k < 2; ++k) \
;         acc[ai][bj][m][n] = __builtin_amdgcn_mfma_f32_16x16x32_bf16(Bt[n][k], At[m][k], acc[ai][bj][m][n], 0, 0, 0); __builtin_amdgcn_s_setprio(0); } while (0)
; #define PG8_WAIT_V(n) asm volatile("s_waitcnt vmcnt(" #n ")" ::: "memory")
; #define PG8_WAIT_L(n) asm volatile("s_waitcnt lgkmcnt(" #n ")" ::: "memory")
; #define PG8_BAR __builtin_amdgcn_s_barrier()
; #define PG8_SCHED __builtin_amdgcn_sched_barrier(0)
; template <class Epi, class Sched, bool ALIGN_EPI = false, bool SP2 = false>
; __device__ __forceinline__ void gemm_phase(PG8_LAS unsigned char* lds, const Gemm g, const Sched& S, const Epi& E, int tid_in) {
;     ...
;             PG8_WAIT_V(8); PG8_WAIT_L(0); PG8_BAR; PG8_MMA(1, 0, At, B0); PG8_MMA(1, 1, At, B1); PG8_BAR; PG8_SCHED;
;             PG8_LDB(B0, 1, 0); PG8_LDB(B1, 1, 1); PG8_SCHED; PG8_LDA(At, 1, 0); PG8_STAGE(PG8_SA(0, 1), a2 + hstepA, voffA);
;             PG8_WAIT_V(8); PG8_WAIT_L(0); PG8_BAR; PG8_MMA(0, 0, At, B0); PG8_MMA(0, 1, At, B1); PG8_BAR; PG8_SCHED;
	s_setprio 1
	v_mfma_f32_16x16x32_bf16 v[92:95], v[96:99], v[178:181], v[92:95]
	v_mfma_f32_16x16x32_bf16 v[88:91], v[150:153], v[178:181], v[88:91]
	v_mfma_f32_16x16x32_bf16 v[84:87], v[96:99], v[186:189], v[84:87]
	v_mfma_f32_16x16x32_bf16 v[80:83], v[150:153], v[186:189], v[80:83]
	v_mfma_f32_16x16x32_bf16 v[76:79], v[96:99], v[204:207], v[76:79]
	v_mfma_f32_16x16x32_bf16 v[72:75], v[150:153], v[204:207], v[72:75]
	v_mfma_f32_16x16x32_bf16 v[68:71], v[96:99], v[212:215], v[68:71]
	v_mfma_f32_16x16x32_bf16 v[64:67], v[150:153], v[212:215], v[64:67]
	v_mfma_f32_16x16x32_bf16 v[92:95], v[100:103], v[182:185], v[92:95]
	v_mfma_f32_16x16x32_bf16 v[88:91], v[158:161], v[182:185], v[88:91]
	v_mfma_f32_16x16x32_bf16 v[84:87], v[100:103], v[200:203], v[84:87]
	v_mfma_f32_16x16x32_bf16 v[80:83], v[158:161], v[200:203], v[80:83]
	v_mfma_f32_16x16x32_bf16 v[76:79], v[100:103], v[208:211], v[76:79]
	v_mfma_f32_16x16x32_bf16 v[72:75], v[158:161], v[208:211], v[72:75]
	v_mfma_f32_16x16x32_bf16 v[68:71], v[100:103], v[216:219], v[68:71]
	v_mfma_f32_16x16x32_bf16 v[64:67], v[158:161], v[216:219], v[64:67]
	s_setprio 0
	s_setprio 1
	v_mfma_f32_16x16x32_bf16 v[28:31], v[162:165], v[178:181], v[28:31]
	v_mfma_f32_16x16x32_bf16 v[24:27], v[170:173], v[178:181], v[24:27]
	v_mfma_f32_16x16x32_bf16 v[20:23], v[162:165], v[186:189], v[20:23]
	v_mfma_f32_16x16x32_bf16 v[16:19], v[170:173], v[186:189], v[16:19]
	v_mfma_f32_16x16x32_bf16 v[12:15], v[162:165], v[204:207], v[12:15]
	v_mfma_f32_16x16x32_bf16 v[8:11], v[170:173], v[204:207], v[8:11]
	v_mfma_f32_16x16x32_bf16 v[4:7], v[162:165], v[212:215], v[4:7]
	v_mfma_f32_16x16x32_bf16 v[0:3], v[170:173], v[212:215], v[0:3]
	v_mfma_f32_16x16x32_bf16 v[28:31], v[166:169], v[182:185], v[28:31]
	v_mfma_f32_16x16x32_bf16 v[24:27], v[174:177], v[182:185], v[24:27]
	v_mfma_f32_16x16x32_bf16 v[20:23], v[166:169], v[200:203], v[20:23]
	v_mfma_f32_16x16x32_bf16 v[16:19], v[174:177], v[200:203], v[16:19]
	v_mfma_f32_16x16x32_bf16 v[12:15], v[166:169], v[208:211], v[12:15]
	v_mfma_f32_16x16x32_bf16 v[8:11], v[174:177], v[208:211], v[8:11]
	v_mfma_f32_16x16x32_bf16 v[4:7], v[166:169], v[216:219], v[4:7]
	v_mfma_f32_16x16x32_bf16 v[0:3], v[174:177], v[216:219], v[0:3]
	s_setprio 0
	s_barrier
	s_add_i32 s54, 0, 0x18000
	s_add_i32 s55, 0, 0x1c000
	v_add_u32_e32 v158, s54, v156
	v_add_u32_e32 v174, s55, v156
	ds_read_b128 v[96:99], v158
	ds_read_b128 v[100:103], v158 offset:1024
	ds_read_b128 v[150:153], v158 offset:2048
	ds_read_b128 v[158:161], v158 offset:3072
	ds_read_b128 v[162:165], v174
	ds_read_b128 v[166:169], v174 offset:1024
	ds_read_b128 v[170:173], v174 offset:2048
	ds_read_b128 v[174:177], v174 offset:3072
	s_add_u32 s28, s28, 0x40000
	s_addc_u32 s29, s29, 0
	s_mov_b32 m0, s41
	ds_read_b128 v[178:181], v157 offset:32768
	ds_read_b128 v[182:185], v157 offset:33792
	ds_read_b128 v[186:189], v157 offset:34816
	ds_read_b128 v[200:203], v157 offset:35840
	ds_read_b128 v[204:207], v157 offset:36864
	ds_read_b128 v[208:211], v157 offset:37888
	ds_read_b128 v[212:215], v157 offset:38912
	ds_read_b128 v[216:219], v157 offset:39936
	global_load_lds_dwordx4 v140, s[28:29]
	s_mov_b32 m0, s42
	s_nop 0
	global_load_lds_dwordx4 v138, s[28:29]
	s_waitcnt vmcnt(8)
	s_waitcnt lgkmcnt(0)
	s_barrier
	s_setprio 1
	v_mfma_f32_16x16x32_bf16 v[132:135], v[96:99], v[178:181], v[132:135]
	v_mfma_f32_16x16x32_bf16 v[128:131], v[150:153], v[178:181], v[128:131]
	v_mfma_f32_16x16x32_bf16 v[124:127], v[96:99], v[186:189], v[124:127]
	v_mfma_f32_16x16x32_bf16 v[120:123], v[150:153], v[186:189], v[120:123]
	v_mfma_f32_16x16x32_bf16 v[116:119], v[96:99], v[204:207], v[116:119]
	v_mfma_f32_16x16x32_bf16 v[112:115], v[150:153], v[204:207], v[112:115]
	v_mfma_f32_16x16x32_bf16 v[108:111], v[96:99], v[212:215], v[108:111]
	v_mfma_f32_16x16x32_bf16 v[104:107], v[150:153], v[212:215], v[104:107]
	v_mfma_f32_16x16x32_bf16 v[132:135], v[100:103], v[182:185], v[132:135]
	v_mfma_f32_16x16x32_bf16 v[128:131], v[158:161], v[182:185], v[128:131]
	v_mfma_f32_16x16x32_bf16 v[124:127], v[100:103], v[200:203], v[124:127]
	v_mfma_f32_16x16x32_bf16 v[120:123], v[158:161], v[200:203], v[120:123]
	v_mfma_f32_16x16x32_bf16 v[116:119], v[100:103], v[208:211], v[116:119]
	v_mfma_f32_16x16x32_bf16 v[112:115], v[158:161], v[208:211], v[112:115]
	v_mfma_f32_16x16x32_bf16 v[108:111], v[100:103], v[216:219], v[108:111]
	v_mfma_f32_16x16x32_bf16 v[104:107], v[158:161], v[216:219], v[104:107]
	s_setprio 0
	s_setprio 1
	v_mfma_f32_16x16x32_bf16 v[60:63], v[162:165], v[178:181], v[60:63]
	v_mfma_f32_16x16x32_bf16 v[56:59], v[170:173], v[178:181], v[56:59]
	v_mfma_f32_16x16x32_bf16 v[52:55], v[162:165], v[186:189], v[52:55]
	v_mfma_f32_16x16x32_bf16 v[48:51], v[170:173], v[186:189], v[48:51]
	v_mfma_f32_16x16x32_bf16 v[44:47], v[162:165], v[204:207], v[44:47]
	v_mfma_f32_16x16x32_bf16 v[40:43], v[170:173], v[204:207], v[40:43]
	v_mfma_f32_16x16x32_bf16 v[36:39], v[162:165], v[212:215], v[36:39]
	v_mfma_f32_16x16x32_bf16 v[32:35], v[170:173], v[212:215], v[32:35]
	v_mfma_f32_16x16x32_bf16 v[60:63], v[166:169], v[182:185], v[60:63]
	v_mfma_f32_16x16x32_bf16 v[56:59], v[174:177], v[182:185], v[56:59]
	v_mfma_f32_16x16x32_bf16 v[52:55], v[166:169], v[200:203], v[52:55]
	v_mfma_f32_16x16x32_bf16 v[48:51], v[174:177], v[200:203], v[48:51]
	v_mfma_f32_16x16x32_bf16 v[44:47], v[166:169], v[208:211], v[44:47]
	v_mfma_f32_16x16x32_bf16 v[40:43], v[174:177], v[208:211], v[40:43]
	v_mfma_f32_16x16x32_bf16 v[36:39], v[166:169], v[216:219], v[36:39]
	v_mfma_f32_16x16x32_bf16 v[32:35], v[174:177], v[216:219], v[32:35]
	s_setprio 0
	s_barrier
; #define PG8_STAGE(bufoff, gbase, voff) do { _Pragma("unroll") for (int _i = 0; _i < 2; ++_i) \
;         __builtin_amdgcn_global_load_lds((const unsigned*)((const char*)(gbase) + (voff)[_i]), (PG8_LAS unsigned*)(lds + (bufoff) + ldsw + _i * 8192), 16, 0, 0); } while (0)
; #define PG8_LDA(dst, b, h) do { _Pragma("unroll") for (int m = 0; m < 4; ++m) _Pragma("unroll") for (int k = 0; k < 2; ++k) dst[m][k] = *(const PG8_LAS bf16x8*)(lds + PG8_SA(b, h) + aoff + m * 2048 + k * 1024); } while (0)
; #define PG8_MMA(ai, bj, At, Bt) do { __builtin_amdgcn_s_setprio(1); _Pragma("unroll") for (int m = 0; m < 4; ++m) _Pragma("unroll") for (int n = 0; n < 2; ++n) _Pragma("unroll") for (int k = 0; k < 2; ++k) \
;         acc[ai][bj][m][n] = __builtin_amdgcn_mfma_f32_16x16x32_bf16(Bt[n][k], At[m][k], acc[ai][bj][m][n], 0, 0, 0); __builtin_amdgcn_s_setprio(0); } while (0)
; #define PG8_WAIT_V(n) asm volatile("s_waitcnt vmcnt(" #n ")" ::: "memory")
; #define PG8_WAIT_L(n) asm volatile("s_waitcnt lgkmcnt(" #n ")" ::: "memory")
; #define PG8_BAR __builtin_amdgcn_s_barrier()
; #define PG8_SCHED __builtin_amdgcn_sched_barrier(0)
; template <class Epi, class Sched, bool ALIGN_EPI = false, bool SP2 = false>
; __device__ __forceinline__ void gemm_phase(PG8_LAS unsigned char* lds, const Gemm g, const Sched& S, const Epi& E, int tid_in) {
;     ...
;             PG8_LDA(At, 1, 1); PG8_STAGE(PG8_SB(1, 0), b3, voffB); PG8_STAGE(PG8_SB(1, 1), b3 + hstep, voffB); PG8_STAGE(PG8_SA(1, 0), a3, voffA);
;             PG8_WAIT_V(8); PG8_WAIT_L(0); PG8_BAR; PG8_MMA(1, 0, At, B0); PG8_MMA(1, 1, At, B1); PG8_BAR; PG8_SCHED;
	s_add_i32 s28, s54, s35
	s_mov_b32 m0, s28
	ds_read_b128 v[178:181], v157 offset:49152
	ds_read_b128 v[182:185], v157 offset:50176
	ds_read_b128 v[186:189], v157 offset:51200
	ds_read_b128 v[200:203], v157 offset:52224
	ds_read_b128 v[204:207], v157 offset:53248
	ds_read_b128 v[208:211], v157 offset:54272
	ds_read_b128 v[212:215], v157 offset:55296
	ds_read_b128 v[216:219], v157 offset:56320
	s_add_u32 s100, s100, 0x80
	s_addc_u32 s101, s101, 0
	global_load_lds_dwordx4 v190, s[100:101]
	s_add_i32 m0, s28, 0x2000
	s_add_u32 s26, s26, 0x80080
	s_addc_u32 s27, s27, 0
	s_add_i32 s28, s55, s35
	global_load_lds_dwordx4 v136, s[100:101]
	s_mov_b32 m0, s28
	s_nop 0
	global_load_lds_dwordx4 v190, s[26:27]
	s_add_i32 m0, s28, 0x2000
	s_nop 0
	global_load_lds_dwordx4 v136, s[26:27]
	v_lshl_add_u64 v[226:227], v[230:231], 0, s[0:1]
	s_mov_b32 m0, s45
	s_nop 0
	global_load_lds_dwordx4 v[226:227], off
	v_lshl_add_u64 v[226:227], v[232:233], 0, s[0:1]
	s_mov_b32 m0, s46
	s_nop 0
	global_load_lds_dwordx4 v[226:227], off
	s_waitcnt vmcnt(8)
	s_waitcnt lgkmcnt(0)
	s_barrier
	s_setprio 1
	v_mfma_f32_16x16x32_bf16 v[92:95], v[96:99], v[178:181], v[92:95]
	v_mfma_f32_16x16x32_bf16 v[88:91], v[150:153], v[178:181], v[88:91]
	v_mfma_f32_16x16x32_bf16 v[84:87], v[96:99], v[186:189], v[84:87]
	v_mfma_f32_16x16x32_bf16 v[80:83], v[150:153], v[186:189], v[80:83]
	v_mfma_f32_16x16x32_bf16 v[76:79], v[96:99], v[204:207], v[76:79]
	v_mfma_f32_16x16x32_bf16 v[72:75], v[150:153], v[204:207], v[72:75]
	v_mfma_f32_16x16x32_bf16 v[68:71], v[96:99], v[212:215], v[68:71]
	v_mfma_f32_16x16x32_bf16 v[64:67], v[150:153], v[212:215], v[64:67]
	v_mfma_f32_16x16x32_bf16 v[92:95], v[100:103], v[182:185], v[92:95]
	v_mfma_f32_16x16x32_bf16 v[88:91], v[158:161], v[182:185], v[88:91]
	v_mfma_f32_16x16x32_bf16 v[84:87], v[100:103], v[200:203], v[84:87]
	v_mfma_f32_16x16x32_bf16 v[80:83], v[158:161], v[200:203], v[80:83]
	v_mfma_f32_16x16x32_bf16 v[76:79], v[100:103], v[208:211], v[76:79]
	v_mfma_f32_16x16x32_bf16 v[72:75], v[158:161], v[208:211], v[72:75]
	v_mfma_f32_16x16x32_bf16 v[68:71], v[100:103], v[216:219], v[68:71]
	v_mfma_f32_16x16x32_bf16 v[64:67], v[158:161], v[216:219], v[64:67]
	s_setprio 0
	s_setprio 1
	v_mfma_f32_16x16x32_bf16 v[28:31], v[162:165], v[178:181], v[28:31]
	v_mfma_f32_16x16x32_bf16 v[24:27], v[170:173], v[178:181], v[24:27]
	v_mfma_f32_16x16x32_bf16 v[20:23], v[162:165], v[186:189], v[20:23]
	v_mfma_f32_16x16x32_bf16 v[16:19], v[170:173], v[186:189], v[16:19]
	v_mfma_f32_16x16x32_bf16 v[12:15], v[162:165], v[204:207], v[12:15]
	v_mfma_f32_16x16x32_bf16 v[8:11], v[170:173], v[204:207], v[8:11]
	v_mfma_f32_16x16x32_bf16 v[4:7], v[162:165], v[212:215], v[4:7]
	v_mfma_f32_16x16x32_bf16 v[0:3], v[170:173], v[212:215], v[0:3]
	v_mfma_f32_16x16x32_bf16 v[28:31], v[166:169], v[182:185], v[28:31]
	v_mfma_f32_16x16x32_bf16 v[24:27], v[174:177], v[182:185], v[24:27]
	v_mfma_f32_16x16x32_bf16 v[20:23], v[166:169], v[200:203], v[20:23]
	v_mfma_f32_16x16x32_bf16 v[16:19], v[174:177], v[200:203], v[16:19]
	v_mfma_f32_16x16x32_bf16 v[12:15], v[166:169], v[208:211], v[12:15]
	v_mfma_f32_16x16x32_bf16 v[8:11], v[174:177], v[208:211], v[8:11]
	v_mfma_f32_16x16x32_bf16 v[4:7], v[166:169], v[216:219], v[4:7]
	v_mfma_f32_16x16x32_bf16 v[0:3], v[174:177], v[216:219], v[0:3]
	s_setprio 0
	s_barrier
	s_add_i32 s53, s53, 2
	s_add_u32 s51, s51, 0x100
	s_addc_u32 s52, s52, 0
	s_add_u32 s24, s24, 0x100
	s_addc_u32 s25, s25, 0
	s_cmp_gt_u32 s53, 29
	s_cbranch_scc0 .LBB0_782
	s_and_b64 vcc, exec, s[8:9]
	s_cbranch_vccz .LBB0_785
	s_barrier

; #define PG8_STAGE(bufoff, gbase, voff) do { _Pragma("unroll") for (int _i = 0; _i < 2; ++_i) \
;         __builtin_amdgcn_global_load_lds((const unsigned*)((const char*)(gbase) + (voff)[_i]), (PG8_LAS unsigned*)(lds + (bufoff) + ldsw + _i * 8192), 16, 0, 0); } while (0)
; #define PG8_LDA(dst, b, h) do { _Pragma("unroll") for (int m = 0; m < 4; ++m) _Pragma("unroll") for (int k = 0; k < 2; ++k) dst[m][k] = *(const PG8_LAS bf16x8*)(lds + PG8_SA(b, h) + aoff + m * 2048 + k * 1024); } while (0)
; #define PG8_LDB(dst, b, h) do { _Pragma("unroll") for (int n = 0; n < 2; ++n) _Pragma("unroll") for (int k = 0; k < 2; ++k) dst[n][k] = *(const PG8_LAS bf16x8*)(lds + PG8_SB(b, h) + boff + n * 2048 + k * 1024); } while (0)
; #define PG8_MMA(ai, bj, At, Bt) do { __builtin_amdgcn_s_setprio(1); _Pragma("unroll") for (int m = 0; m < 4; ++m) _Pragma("unroll") for (int n = 0; n < 2; ++n) _Pragma("unroll") for (int k = 0; k < 2; ++k) \
;         acc[ai][bj][m][n] = __builtin_amdgcn_mfma_f32_16x16x32_bf16(Bt[n][k], At[m][k], acc[ai][bj][m][n], 0, 0, 0); __builtin_amdgcn_s_setprio(0); } while (0)
; #define PG8_WAIT_V(n) asm volatile("s_waitcnt vmcnt(" #n ")" ::: "memory")
; #define PG8_WAIT_L(n) asm volatile("s_waitcnt lgkmcnt(" #n ")" ::: "memory")
; template <class Epi, class Sched, bool ALIGN_EPI = false, bool SP2 = false>
; __device__ __forceinline__ void gemm_phase(PG8_LAS unsigned char* lds, const Gemm g, const Sched& S, const Epi& E, int tid_in) {
;     ...
;             const bool last = (t == nt - 2);
;             const char* a1 = cA + (size_t)(t + 1) * kstep;
;             const char* a2 = last ? nA : cA + (size_t)(t + 2) * kstep; const char* b2 = last ? nB : cB + (size_t)(t + 2) * kstep;
;             const char* a3 = a2 + kstep; const char* b3 = b2 + kstep;
;             if (last && has_next) S.a_ready(nxt);
;             if constexpr (SP2) {
;             PG8_LDB(B0, 0, 0); PG8_LDB(B1, 0, 1); PG8_SCHED; PG8_LDA(At, 0, 0); PG8_STAGE(PG8_SA(1, 1), a1 + hstepA, voffA);
;             PG8_WAIT_V(8); PG8_WAIT_L(0); PG8_BAR; PG8_MMA(0, 0, At, B0); PG8_MMA(0, 1, At, B1); PG8_BAR; PG8_SCHED;
;             PG8_LDA(At, 0, 1); PG8_STAGE(PG8_SB(0, 0), b2, voffB); PG8_STAGE(PG8_SB(0, 1), b2 + hstep, voffB); PG8_STAGE(PG8_SA(0, 0), a2, voffA);
;             PG8_WAIT_V(8); PG8_WAIT_L(0); PG8_BAR; PG8_MMA(1, 0, At, B0); PG8_MMA(1, 1, At, B1); PG8_BAR; PG8_SCHED;
.LBB0_1283:
	s_add_u32 s14, s12, 0xfffc0080
	s_addc_u32 s15, s13, -1
	s_add_i32 s60, 0, 0x10000
	s_cmp_eq_u32 s59, 12
	s_cselect_b32 s27, s19, s15
	s_cselect_b32 s26, s55, s14
	s_cselect_b32 s15, s11, s58
	s_cselect_b32 s14, s56, s57
	s_add_i32 s62, 0, 0x14000
	v_add_u32_e32 v124, s60, v226
	v_add_u32_e32 v140, s62, v226
	ds_read_b128 v[112:115], v124
	ds_read_b128 v[116:119], v124 offset:1024
	ds_read_b128 v[120:123], v124 offset:2048
	ds_read_b128 v[124:127], v124 offset:3072
	ds_read_b128 v[128:131], v140
	ds_read_b128 v[132:135], v140 offset:1024
	ds_read_b128 v[136:139], v140 offset:2048
	ds_read_b128 v[140:143], v140 offset:3072
	s_add_i32 m0, s35, 0xc000
	ds_read_b128 v[144:147], v227
	ds_read_b128 v[148:151], v227 offset:1024
	ds_read_b128 v[152:155], v227 offset:2048
	ds_read_b128 v[156:159], v227 offset:3072
	ds_read_b128 v[176:179], v227 offset:4096
	ds_read_b128 v[180:183], v227 offset:5120
	ds_read_b128 v[208:211], v227 offset:6144
	ds_read_b128 v[212:215], v227 offset:7168
	global_load_lds_dwordx4 v206, s[12:13]
	s_add_i32 m0, s35, 0xe000
	s_nop 0
	global_load_lds_dwordx4 v204, s[12:13]
	s_waitcnt vmcnt(8)
	s_waitcnt lgkmcnt(0)
	s_barrier
	s_setprio 1
	v_mfma_f32_16x16x32_bf16 v[172:175], v[112:115], v[144:147], v[172:175]
	v_mfma_f32_16x16x32_bf16 v[168:171], v[120:123], v[144:147], v[168:171]
	v_mfma_f32_16x16x32_bf16 v[108:111], v[112:115], v[152:155], v[108:111]
	v_mfma_f32_16x16x32_bf16 v[104:107], v[120:123], v[152:155], v[104:107]
	v_mfma_f32_16x16x32_bf16 v[92:95], v[112:115], v[176:179], v[92:95]
	v_mfma_f32_16x16x32_bf16 v[88:91], v[120:123], v[176:179], v[88:91]
	v_mfma_f32_16x16x32_bf16 v[76:79], v[112:115], v[208:211], v[76:79]
	v_mfma_f32_16x16x32_bf16 v[72:75], v[120:123], v[208:211], v[72:75]
	v_mfma_f32_16x16x32_bf16 v[172:175], v[116:119], v[148:151], v[172:175]
	v_mfma_f32_16x16x32_bf16 v[168:171], v[124:127], v[148:151], v[168:171]
	v_mfma_f32_16x16x32_bf16 v[108:111], v[116:119], v[156:159], v[108:111]
	v_mfma_f32_16x16x32_bf16 v[104:107], v[124:127], v[156:159], v[104:107]
	v_mfma_f32_16x16x32_bf16 v[92:95], v[116:119], v[180:183], v[92:95]
	v_mfma_f32_16x16x32_bf16 v[88:91], v[124:127], v[180:183], v[88:91]
	v_mfma_f32_16x16x32_bf16 v[76:79], v[116:119], v[212:215], v[76:79]
	v_mfma_f32_16x16x32_bf16 v[72:75], v[124:127], v[212:215], v[72:75]
	s_setprio 0
	s_setprio 1
	v_mfma_f32_16x16x32_bf16 v[164:167], v[128:131], v[144:147], v[164:167]
	v_mfma_f32_16x16x32_bf16 v[100:103], v[128:131], v[152:155], v[100:103]
	v_mfma_f32_16x16x32_bf16 v[96:99], v[136:139], v[152:155], v[96:99]
	v_mfma_f32_16x16x32_bf16 v[84:87], v[128:131], v[176:179], v[84:87]
	v_mfma_f32_16x16x32_bf16 v[80:83], v[136:139], v[176:179], v[80:83]
	v_mfma_f32_16x16x32_bf16 v[68:71], v[128:131], v[208:211], v[68:71]
	v_mfma_f32_16x16x32_bf16 v[64:67], v[136:139], v[208:211], v[64:67]
	v_mfma_f32_16x16x32_bf16 v[164:167], v[132:135], v[148:151], v[164:167]
	v_mfma_f32_16x16x32_bf16 v[144:147], v[136:139], v[144:147], v[160:163]
	v_mfma_f32_16x16x32_bf16 v[100:103], v[132:135], v[156:159], v[100:103]
	v_mfma_f32_16x16x32_bf16 v[96:99], v[140:143], v[156:159], v[96:99]
	v_mfma_f32_16x16x32_bf16 v[84:87], v[132:135], v[180:183], v[84:87]
	v_mfma_f32_16x16x32_bf16 v[80:83], v[140:143], v[180:183], v[80:83]
	v_mfma_f32_16x16x32_bf16 v[68:71], v[132:135], v[212:215], v[68:71]
	v_mfma_f32_16x16x32_bf16 v[64:67], v[140:143], v[212:215], v[64:67]
	v_mfma_f32_16x16x32_bf16 v[144:147], v[140:143], v[148:151], v[144:147]
	s_setprio 0
	s_barrier
	s_add_i32 s60, s60, s34
	s_mov_b32 m0, s60
	ds_read_b128 v[148:151], v227 offset:16384
	ds_read_b128 v[152:155], v227 offset:17408
	ds_read_b128 v[156:159], v227 offset:18432
	ds_read_b128 v[160:163], v227 offset:19456
	ds_read_b128 v[176:179], v227 offset:20480
	ds_read_b128 v[180:183], v227 offset:21504
	ds_read_b128 v[208:211], v227 offset:22528
	ds_read_b128 v[212:215], v227 offset:23552
	global_load_lds_dwordx4 v190, s[14:15]
	s_add_i32 m0, s60, 0x2000
	s_add_u32 s60, s14, 0x40000
	s_addc_u32 s61, s15, 0
	s_add_i32 s62, s62, s34
	global_load_lds_dwordx4 v184, s[14:15]
	s_mov_b32 m0, s62
	s_mov_b64 s[100:101], s[26:27]
	global_load_lds_dwordx4 v190, s[60:61]
	s_add_i32 m0, s62, 0x2000
	s_nop 0
	global_load_lds_dwordx4 v184, s[60:61]
	s_mov_b32 m0, s35
	s_nop 0
	global_load_lds_dwordx4 v188, s[100:101]
	s_mov_b32 m0, s46
	s_nop 0
	global_load_lds_dwordx4 v186, s[100:101]
	s_waitcnt vmcnt(8)
	s_waitcnt lgkmcnt(0)
	s_barrier
	s_setprio 1
	v_mfma_f32_16x16x32_bf16 v[60:63], v[112:115], v[148:151], v[60:63]
	v_mfma_f32_16x16x32_bf16 v[56:59], v[120:123], v[148:151], v[56:59]
	v_mfma_f32_16x16x32_bf16 v[44:47], v[112:115], v[156:159], v[44:47]
	v_mfma_f32_16x16x32_bf16 v[40:43], v[120:123], v[156:159], v[40:43]
	v_mfma_f32_16x16x32_bf16 v[28:31], v[112:115], v[176:179], v[28:31]
	v_mfma_f32_16x16x32_bf16 v[24:27], v[120:123], v[176:179], v[24:27]
	v_mfma_f32_16x16x32_bf16 v[12:15], v[112:115], v[208:211], v[12:15]
	v_mfma_f32_16x16x32_bf16 v[8:11], v[120:123], v[208:211], v[8:11]
	v_mfma_f32_16x16x32_bf16 v[60:63], v[116:119], v[152:155], v[60:63]
	v_mfma_f32_16x16x32_bf16 v[56:59], v[124:127], v[152:155], v[56:59]
	v_mfma_f32_16x16x32_bf16 v[44:47], v[116:119], v[160:163], v[44:47]
	v_mfma_f32_16x16x32_bf16 v[40:43], v[124:127], v[160:163], v[40:43]
	v_mfma_f32_16x16x32_bf16 v[28:31], v[116:119], v[180:183], v[28:31]
	v_mfma_f32_16x16x32_bf16 v[24:27], v[124:127], v[180:183], v[24:27]
	v_mfma_f32_16x16x32_bf16 v[12:15], v[116:119], v[212:215], v[12:15]
	v_mfma_f32_16x16x32_bf16 v[8:11], v[124:127], v[212:215], v[8:11]
	s_setprio 0
	s_setprio 1
	v_mfma_f32_16x16x32_bf16 v[52:55], v[128:131], v[148:151], v[52:55]
	v_mfma_f32_16x16x32_bf16 v[48:51], v[136:139], v[148:151], v[48:51]
	v_mfma_f32_16x16x32_bf16 v[36:39], v[128:131], v[156:159], v[36:39]
	v_mfma_f32_16x16x32_bf16 v[32:35], v[136:139], v[156:159], v[32:35]
	v_mfma_f32_16x16x32_bf16 v[20:23], v[128:131], v[176:179], v[20:23]
	v_mfma_f32_16x16x32_bf16 v[16:19], v[136:139], v[176:179], v[16:19]
	v_mfma_f32_16x16x32_bf16 v[4:7], v[128:131], v[208:211], v[4:7]
	v_mfma_f32_16x16x32_bf16 v[0:3], v[136:139], v[208:211], v[0:3]
	v_mfma_f32_16x16x32_bf16 v[52:55], v[132:135], v[152:155], v[52:55]
	v_mfma_f32_16x16x32_bf16 v[48:51], v[140:143], v[152:155], v[48:51]
	v_mfma_f32_16x16x32_bf16 v[36:39], v[132:135], v[160:163], v[36:39]
	v_mfma_f32_16x16x32_bf16 v[32:35], v[140:143], v[160:163], v[32:35]
	v_mfma_f32_16x16x32_bf16 v[20:23], v[132:135], v[180:183], v[20:23]
	v_mfma_f32_16x16x32_bf16 v[16:19], v[140:143], v[180:183], v[16:19]
	v_mfma_f32_16x16x32_bf16 v[4:7], v[132:135], v[212:215], v[4:7]
	v_mfma_f32_16x16x32_bf16 v[0:3], v[140:143], v[212:215], v[0:3]
	s_setprio 0
	s_barrier
; #define PG8_STAGE(bufoff, gbase, voff) do { _Pragma("unroll") for (int _i = 0; _i < 2; ++_i) \
;         __builtin_amdgcn_global_load_lds((const unsigned*)((const char*)(gbase) + (voff)[_i]), (PG8_LAS unsigned*)(lds + (bufoff) + ldsw + _i * 8192), 16, 0, 0); } while (0)
; #define PG8_LDA(dst, b, h) do { _Pragma("unroll") for (int m = 0; m < 4; ++m) _Pragma("unroll") for (int k = 0; k < 2; ++k) dst[m][k] = *(const PG8_LAS bf16x8*)(lds + PG8_SA(b, h) + aoff + m * 2048 + k * 1024); } while (0)
; #define PG8_LDB(dst, b, h) do { _Pragma("unroll") for (int n = 0; n < 2; ++n) _Pragma("unroll") for (int k = 0; k < 2; ++k) dst[n][k] = *(const PG8_LAS bf16x8*)(lds + PG8_SB(b, h) + boff + n * 2048 + k * 1024); } while (0)
; #define PG8_MMA(ai, bj, At, Bt) do { __builtin_amdgcn_s_setprio(1); _Pragma("unroll") for (int m = 0; m < 4; ++m) _Pragma("unroll") for (int n = 0; n < 2; ++n) _Pragma("unroll") for (int k = 0; k < 2; ++k) \
;         acc[ai][bj][m][n] = __builtin_amdgcn_mfma_f32_16x16x32_bf16(Bt[n][k], At[m][k], acc[ai][bj][m][n], 0, 0, 0); __builtin_amdgcn_s_setprio(0); } while (0)
; #define PG8_WAIT_V(n) asm volatile("s_waitcnt vmcnt(" #n ")" ::: "memory")
; #define PG8_WAIT_L(n) asm volatile("s_waitcnt lgkmcnt(" #n ")" ::: "memory")
; #define PG8_BAR __builtin_amdgcn_s_barrier()
; #define PG8_SCHED __builtin_amdgcn_sched_barrier(0)
; template <class Epi, class Sched, bool ALIGN_EPI = false, bool SP2 = false>
; __device__ __forceinline__ void gemm_phase(PG8_LAS unsigned char* lds, const Gemm g, const Sched& S, const Epi& E, int tid_in) {
;     ...
;             PG8_LDB(B0, 1, 0); PG8_LDB(B1, 1, 1); PG8_SCHED; PG8_LDA(At, 1, 0); PG8_STAGE(PG8_SA(0, 1), a2 + hstepA, voffA);
;             PG8_WAIT_V(8); PG8_WAIT_L(0); PG8_BAR; PG8_MMA(0, 0, At, B0); PG8_MMA(0, 1, At, B1); PG8_BAR; PG8_SCHED;
;             PG8_LDA(At, 1, 1); PG8_STAGE(PG8_SB(1, 0), b3, voffB); PG8_STAGE(PG8_SB(1, 1), b3 + hstep, voffB); PG8_STAGE(PG8_SA(1, 0), a3, voffA);
;             PG8_WAIT_V(8); PG8_WAIT_L(0); PG8_BAR; PG8_MMA(1, 0, At, B0); PG8_MMA(1, 1, At, B1); PG8_BAR; PG8_SCHED;
	s_add_i32 s60, 0, 0x18000
	s_add_i32 s61, 0, 0x1c000
	v_add_u32_e32 v124, s60, v226
	v_add_u32_e32 v140, s61, v226
	ds_read_b128 v[112:115], v124
	ds_read_b128 v[116:119], v124 offset:1024
	ds_read_b128 v[120:123], v124 offset:2048
	ds_read_b128 v[124:127], v124 offset:3072
	ds_read_b128 v[128:131], v140
	ds_read_b128 v[132:135], v140 offset:1024
	ds_read_b128 v[136:139], v140 offset:2048
	ds_read_b128 v[140:143], v140 offset:3072
	s_add_u32 s26, s26, 0x40000
	s_addc_u32 s27, s27, 0
	s_mov_b32 m0, s47
	ds_read_b128 v[148:151], v227 offset:32768
	ds_read_b128 v[152:155], v227 offset:33792
	ds_read_b128 v[156:159], v227 offset:34816
	ds_read_b128 v[176:179], v227 offset:35840
	ds_read_b128 v[180:183], v227 offset:36864
	ds_read_b128 v[208:211], v227 offset:37888
	ds_read_b128 v[212:215], v227 offset:38912
	ds_read_b128 v[216:219], v227 offset:39936
	global_load_lds_dwordx4 v188, s[26:27]
	s_mov_b32 m0, s49
	s_nop 0
	global_load_lds_dwordx4 v186, s[26:27]
	s_waitcnt vmcnt(8)
	s_waitcnt lgkmcnt(0)
	s_barrier
	s_setprio 1
	v_mfma_f32_16x16x32_bf16 v[160:163], v[112:115], v[148:151], v[172:175]
	v_mfma_f32_16x16x32_bf16 v[172:175], v[116:119], v[152:155], v[160:163]
	v_mfma_f32_16x16x32_bf16 v[160:163], v[120:123], v[148:151], v[168:171]
	v_mfma_f32_16x16x32_bf16 v[108:111], v[112:115], v[156:159], v[108:111]
	v_mfma_f32_16x16x32_bf16 v[104:107], v[120:123], v[156:159], v[104:107]
	v_mfma_f32_16x16x32_bf16 v[92:95], v[112:115], v[180:183], v[92:95]
	v_mfma_f32_16x16x32_bf16 v[88:91], v[120:123], v[180:183], v[88:91]
	v_mfma_f32_16x16x32_bf16 v[76:79], v[112:115], v[212:215], v[76:79]
	v_mfma_f32_16x16x32_bf16 v[72:75], v[120:123], v[212:215], v[72:75]
	v_mfma_f32_16x16x32_bf16 v[168:171], v[124:127], v[152:155], v[160:163]
	v_mfma_f32_16x16x32_bf16 v[108:111], v[116:119], v[176:179], v[108:111]
	v_mfma_f32_16x16x32_bf16 v[104:107], v[124:127], v[176:179], v[104:107]
	v_mfma_f32_16x16x32_bf16 v[92:95], v[116:119], v[208:211], v[92:95]
	v_mfma_f32_16x16x32_bf16 v[88:91], v[124:127], v[208:211], v[88:91]
	v_mfma_f32_16x16x32_bf16 v[76:79], v[116:119], v[216:219], v[76:79]
	v_mfma_f32_16x16x32_bf16 v[72:75], v[124:127], v[216:219], v[72:75]
	s_setprio 0
	s_setprio 1
	v_mfma_f32_16x16x32_bf16 v[160:163], v[128:131], v[148:151], v[164:167]
	v_mfma_f32_16x16x32_bf16 v[144:147], v[136:139], v[148:151], v[144:147]
	v_mfma_f32_16x16x32_bf16 v[100:103], v[128:131], v[156:159], v[100:103]
	v_mfma_f32_16x16x32_bf16 v[96:99], v[136:139], v[156:159], v[96:99]
	v_mfma_f32_16x16x32_bf16 v[84:87], v[128:131], v[180:183], v[84:87]
	v_mfma_f32_16x16x32_bf16 v[80:83], v[136:139], v[180:183], v[80:83]
	v_mfma_f32_16x16x32_bf16 v[68:71], v[128:131], v[212:215], v[68:71]
	v_mfma_f32_16x16x32_bf16 v[64:67], v[136:139], v[212:215], v[64:67]
	v_mfma_f32_16x16x32_bf16 v[164:167], v[132:135], v[152:155], v[160:163]
	v_mfma_f32_16x16x32_bf16 v[160:163], v[140:143], v[152:155], v[144:147]
	v_mfma_f32_16x16x32_bf16 v[100:103], v[132:135], v[176:179], v[100:103]
	v_mfma_f32_16x16x32_bf16 v[96:99], v[140:143], v[176:179], v[96:99]
	v_mfma_f32_16x16x32_bf16 v[84:87], v[132:135], v[208:211], v[84:87]
	v_mfma_f32_16x16x32_bf16 v[80:83], v[140:143], v[208:211], v[80:83]
	v_mfma_f32_16x16x32_bf16 v[68:71], v[132:135], v[216:219], v[68:71]
	v_mfma_f32_16x16x32_bf16 v[64:67], v[140:143], v[216:219], v[64:67]
	s_setprio 0
	s_barrier
	s_add_i32 s26, s60, s34
	s_mov_b32 m0, s26
	ds_read_b128 v[144:147], v227 offset:49152
	ds_read_b128 v[148:151], v227 offset:50176
	ds_read_b128 v[152:155], v227 offset:51200
	ds_read_b128 v[156:159], v227 offset:52224
	ds_read_b128 v[176:179], v227 offset:53248
	ds_read_b128 v[180:183], v227 offset:54272
	ds_read_b128 v[208:211], v227 offset:55296
	ds_read_b128 v[212:215], v227 offset:56320
	s_add_u32 s14, s14, 0x80
	s_addc_u32 s15, s15, 0
	global_load_lds_dwordx4 v190, s[14:15]
	s_add_i32 m0, s26, 0x2000
	s_nop 0
	global_load_lds_dwordx4 v184, s[14:15]
	s_add_u32 s14, s14, 0x40000
	s_addc_u32 s15, s15, 0
	s_add_i32 s26, s61, s34
	s_mov_b32 m0, s26
	s_nop 0
	global_load_lds_dwordx4 v190, s[14:15]
	s_add_i32 m0, s26, 0x2000
	s_nop 0
	global_load_lds_dwordx4 v184, s[14:15]
	s_mov_b32 m0, s52
	s_nop 0
	s_add_u32 s100, s100, 0x80
	s_addc_u32 s101, s101, 0
	global_load_lds_dwordx4 v188, s[100:101]
	s_mov_b32 m0, s53
	s_nop 0
	global_load_lds_dwordx4 v186, s[100:101]
	s_waitcnt vmcnt(8)
	s_waitcnt lgkmcnt(0)
	s_barrier
	s_setprio 1
	v_mfma_f32_16x16x32_bf16 v[60:63], v[112:115], v[144:147], v[60:63]
	v_mfma_f32_16x16x32_bf16 v[56:59], v[120:123], v[144:147], v[56:59]
	v_mfma_f32_16x16x32_bf16 v[44:47], v[112:115], v[152:155], v[44:47]
	v_mfma_f32_16x16x32_bf16 v[40:43], v[120:123], v[152:155], v[40:43]
	v_mfma_f32_16x16x32_bf16 v[28:31], v[112:115], v[176:179], v[28:31]
	v_mfma_f32_16x16x32_bf16 v[24:27], v[120:123], v[176:179], v[24:27]
	v_mfma_f32_16x16x32_bf16 v[12:15], v[112:115], v[208:211], v[12:15]
	v_mfma_f32_16x16x32_bf16 v[8:11], v[120:123], v[208:211], v[8:11]
	v_mfma_f32_16x16x32_bf16 v[60:63], v[116:119], v[148:151], v[60:63]
	v_mfma_f32_16x16x32_bf16 v[56:59], v[124:127], v[148:151], v[56:59]
	v_mfma_f32_16x16x32_bf16 v[44:47], v[116:119], v[156:159], v[44:47]
	v_mfma_f32_16x16x32_bf16 v[40:43], v[124:127], v[156:159], v[40:43]
	v_mfma_f32_16x16x32_bf16 v[28:31], v[116:119], v[180:183], v[28:31]
	v_mfma_f32_16x16x32_bf16 v[24:27], v[124:127], v[180:183], v[24:27]
	v_mfma_f32_16x16x32_bf16 v[12:15], v[116:119], v[212:215], v[12:15]
	v_mfma_f32_16x16x32_bf16 v[8:11], v[124:127], v[212:215], v[8:11]
	s_setprio 0
	s_setprio 1
	v_mfma_f32_16x16x32_bf16 v[52:55], v[128:131], v[144:147], v[52:55]
	v_mfma_f32_16x16x32_bf16 v[48:51], v[136:139], v[144:147], v[48:51]
	v_mfma_f32_16x16x32_bf16 v[36:39], v[128:131], v[152:155], v[36:39]
	v_mfma_f32_16x16x32_bf16 v[32:35], v[136:139], v[152:155], v[32:35]
	v_mfma_f32_16x16x32_bf16 v[20:23], v[128:131], v[176:179], v[20:23]
	v_mfma_f32_16x16x32_bf16 v[16:19], v[136:139], v[176:179], v[16:19]
	v_mfma_f32_16x16x32_bf16 v[4:7], v[128:131], v[208:211], v[4:7]
	v_mfma_f32_16x16x32_bf16 v[0:3], v[136:139], v[208:211], v[0:3]
	v_mfma_f32_16x16x32_bf16 v[52:55], v[132:135], v[148:151], v[52:55]
	v_mfma_f32_16x16x32_bf16 v[48:51], v[140:143], v[148:151], v[48:51]
	v_mfma_f32_16x16x32_bf16 v[36:39], v[132:135], v[156:159], v[36:39]
	v_mfma_f32_16x16x32_bf16 v[32:35], v[140:143], v[156:159], v[32:35]
	v_mfma_f32_16x16x32_bf16 v[20:23], v[132:135], v[180:183], v[20:23]
	v_mfma_f32_16x16x32_bf16 v[16:19], v[140:143], v[180:183], v[16:19]
	v_mfma_f32_16x16x32_bf16 v[4:7], v[132:135], v[212:215], v[4:7]
	v_mfma_f32_16x16x32_bf16 v[0:3], v[140:143], v[212:215], v[0:3]
	s_setprio 0
	s_barrier
	s_add_i32 s59, s59, 2
	s_add_u32 s57, s57, 0x100
	s_addc_u32 s58, s58, 0
	s_add_u32 s12, s12, 0x100
	s_addc_u32 s13, s13, 0
	s_cmp_gt_u32 s59, 13
	s_cbranch_scc0 .LBB0_1283
	s_and_b64 vcc, exec, s[8:9]
	s_cbranch_vccz .LBB0_1286
	s_barrier

; #define PG8_STAGE(bufoff, gbase, voff) do { _Pragma("unroll") for (int _i = 0; _i < 2; ++_i) \
;         __builtin_amdgcn_global_load_lds((const unsigned*)((const char*)(gbase) + (voff)[_i]), (PG8_LAS unsigned*)(lds + (bufoff) + ldsw + _i * 8192), 16, 0, 0); } while (0)
; #define PG8_LDA(dst, b, h) do { _Pragma("unroll") for (int m = 0; m < 4; ++m) _Pragma("unroll") for (int k = 0; k < 2; ++k) dst[m][k] = *(const PG8_LAS bf16x8*)(lds + PG8_SA(b, h) + aoff + m * 2048 + k * 1024); } while (0)
; #define PG8_LDB(dst, b, h) do { _Pragma("unroll") for (int n = 0; n < 2; ++n) _Pragma("unroll") for (int k = 0; k < 2; ++k) dst[n][k] = *(const PG8_LAS bf16x8*)(lds + PG8_SB(b, h) + boff + n * 2048 + k * 1024); } while (0)
; #define PG8_MMA(ai, bj, At, Bt) do { __builtin_amdgcn_s_setprio(1); _Pragma("unroll") for (int m = 0; m < 4; ++m) _Pragma("unroll") for (int n = 0; n < 2; ++n) _Pragma("unroll") for (int k = 0; k < 2; ++k) \
;         acc[ai][bj][m][n] = __builtin_amdgcn_mfma_f32_16x16x32_bf16(Bt[n][k], At[m][k], acc[ai][bj][m][n], 0, 0, 0); __builtin_amdgcn_s_setprio(0); } while (0)
; #define PG8_WAIT_V(n) asm volatile("s_waitcnt vmcnt(" #n ")" ::: "memory")
; #define PG8_WAIT_L(n) asm volatile("s_waitcnt lgkmcnt(" #n ")" ::: "memory")
; template <class Epi, class Sched, bool ALIGN_EPI = false, bool SP2 = false>
; __device__ __forceinline__ void gemm_phase(PG8_LAS unsigned char* lds, const Gemm g, const Sched& S, const Epi& E, int tid_in) {
;     ...
;             const bool last = (t == nt - 2);
;             const char* a1 = cA + (size_t)(t + 1) * kstep;
;             const char* a2 = last ? nA : cA + (size_t)(t + 2) * kstep; const char* b2 = last ? nB : cB + (size_t)(t + 2) * kstep;
;             const char* a3 = a2 + kstep; const char* b3 = b2 + kstep;
;             if (last && has_next) S.a_ready(nxt);
;             if constexpr (SP2) {
;             PG8_LDB(B0, 0, 0); PG8_LDB(B1, 0, 1); PG8_SCHED; PG8_LDA(At, 0, 0); PG8_STAGE(PG8_SA(1, 1), a1 + hstepA, voffA);
;             PG8_WAIT_V(8); PG8_WAIT_L(0); PG8_BAR; PG8_MMA(0, 0, At, B0); PG8_MMA(0, 1, At, B1); PG8_BAR; PG8_SCHED;
;             PG8_LDA(At, 0, 1); PG8_STAGE(PG8_SB(0, 0), b2, voffB); PG8_STAGE(PG8_SB(0, 1), b2 + hstep, voffB); PG8_STAGE(PG8_SA(0, 0), a2, voffA);
;             PG8_WAIT_V(8); PG8_WAIT_L(0); PG8_BAR; PG8_MMA(1, 0, At, B0); PG8_MMA(1, 1, At, B1); PG8_BAR; PG8_SCHED;
.LBB0_1385:
	s_add_u32 s12, s2, 0xfffc0080
	s_addc_u32 s13, s3, -1
	s_add_i32 s58, 0, 0x10000
	s_cmp_eq_u32 s57, 12
	s_cselect_b32 s15, s21, s13
	s_cselect_b32 s14, s53, s12
	v_add_u32_e32 v140, s58, v145
	s_cselect_b32 s13, s19, s56
	s_cselect_b32 s12, s54, s55
	s_add_i32 s60, 0, 0x14000
	ds_read_b128 v[148:151], v140
	ds_read_b128 v[152:155], v140 offset:1024
	ds_read_b128 v[156:159], v140 offset:2048
	ds_read_b128 v[160:163], v140 offset:3072
	v_add_u32_e32 v140, s60, v145
	ds_read_b128 v[164:167], v140
	ds_read_b128 v[168:171], v140 offset:1024
	ds_read_b128 v[172:175], v140 offset:2048
	ds_read_b128 v[176:179], v140 offset:3072
	s_add_i32 m0, s45, 0xc000
	ds_read_b128 v[180:183], v146
	ds_read_b128 v[184:187], v146 offset:1024
	ds_read_b128 v[200:203], v146 offset:2048
	ds_read_b128 v[204:207], v146 offset:3072
	ds_read_b128 v[208:211], v146 offset:4096
	ds_read_b128 v[212:215], v146 offset:5120
	ds_read_b128 v[216:219], v146 offset:6144
	ds_read_b128 v[226:229], v146 offset:7168
	global_load_lds_dwordx4 v138, s[2:3]
	s_add_i32 m0, s45, 0xe000
	s_nop 0
	global_load_lds_dwordx4 v136, s[2:3]
	s_waitcnt vmcnt(8)
	s_waitcnt lgkmcnt(0)
	s_barrier
	s_setprio 1
	v_mfma_f32_16x16x32_bf16 v[124:127], v[148:151], v[180:183], v[124:127]
	v_mfma_f32_16x16x32_bf16 v[116:119], v[156:159], v[180:183], v[116:119]
	v_mfma_f32_16x16x32_bf16 v[108:111], v[148:151], v[200:203], v[108:111]
	v_mfma_f32_16x16x32_bf16 v[100:103], v[156:159], v[200:203], v[100:103]
	v_mfma_f32_16x16x32_bf16 v[92:95], v[148:151], v[208:211], v[92:95]
	v_mfma_f32_16x16x32_bf16 v[84:87], v[156:159], v[208:211], v[84:87]
	v_mfma_f32_16x16x32_bf16 v[76:79], v[148:151], v[216:219], v[76:79]
	v_mfma_f32_16x16x32_bf16 v[68:71], v[156:159], v[216:219], v[68:71]
	v_mfma_f32_16x16x32_bf16 v[124:127], v[152:155], v[184:187], v[124:127]
	v_mfma_f32_16x16x32_bf16 v[116:119], v[160:163], v[184:187], v[116:119]
	v_mfma_f32_16x16x32_bf16 v[108:111], v[152:155], v[204:207], v[108:111]
	v_mfma_f32_16x16x32_bf16 v[100:103], v[160:163], v[204:207], v[100:103]
	v_mfma_f32_16x16x32_bf16 v[92:95], v[152:155], v[212:215], v[92:95]
	v_mfma_f32_16x16x32_bf16 v[84:87], v[160:163], v[212:215], v[84:87]
	v_mfma_f32_16x16x32_bf16 v[76:79], v[152:155], v[226:229], v[76:79]
	v_mfma_f32_16x16x32_bf16 v[68:71], v[160:163], v[226:229], v[68:71]
	s_setprio 0
	s_setprio 1
	v_mfma_f32_16x16x32_bf16 v[120:123], v[164:167], v[180:183], v[120:123]
	v_mfma_f32_16x16x32_bf16 v[112:115], v[172:175], v[180:183], v[112:115]
	v_mfma_f32_16x16x32_bf16 v[104:107], v[164:167], v[200:203], v[104:107]
	v_mfma_f32_16x16x32_bf16 v[96:99], v[172:175], v[200:203], v[96:99]
	v_mfma_f32_16x16x32_bf16 v[88:91], v[164:167], v[208:211], v[88:91]
	v_mfma_f32_16x16x32_bf16 v[80:83], v[172:175], v[208:211], v[80:83]
	v_mfma_f32_16x16x32_bf16 v[72:75], v[164:167], v[216:219], v[72:75]
	v_mfma_f32_16x16x32_bf16 v[64:67], v[172:175], v[216:219], v[64:67]
	v_mfma_f32_16x16x32_bf16 v[120:123], v[168:171], v[184:187], v[120:123]
	v_mfma_f32_16x16x32_bf16 v[112:115], v[176:179], v[184:187], v[112:115]
	v_mfma_f32_16x16x32_bf16 v[104:107], v[168:171], v[204:207], v[104:107]
	v_mfma_f32_16x16x32_bf16 v[96:99], v[176:179], v[204:207], v[96:99]
	v_mfma_f32_16x16x32_bf16 v[88:91], v[168:171], v[212:215], v[88:91]
	v_mfma_f32_16x16x32_bf16 v[80:83], v[176:179], v[212:215], v[80:83]
	v_mfma_f32_16x16x32_bf16 v[72:75], v[168:171], v[226:229], v[72:75]
	v_mfma_f32_16x16x32_bf16 v[64:67], v[176:179], v[226:229], v[64:67]
	s_setprio 0
	s_barrier
	s_add_i32 s58, s58, s44
	s_mov_b32 m0, s58
	ds_read_b128 v[180:183], v146 offset:16384
	ds_read_b128 v[184:187], v146 offset:17408
	ds_read_b128 v[200:203], v146 offset:18432
	ds_read_b128 v[204:207], v146 offset:19456
	ds_read_b128 v[208:211], v146 offset:20480
	ds_read_b128 v[212:215], v146 offset:21504
	ds_read_b128 v[216:219], v146 offset:22528
	ds_read_b128 v[226:229], v146 offset:23552
	global_load_lds_dwordx4 v132, s[12:13]
	s_add_i32 m0, s58, 0x2000
	s_add_u32 s58, s12, 0x40000
	s_addc_u32 s59, s13, 0
	s_add_i32 s60, s60, s44
	global_load_lds_dwordx4 v128, s[12:13]
	s_mov_b32 m0, s60
	s_mov_b64 s[100:101], s[14:15]
	global_load_lds_dwordx4 v132, s[58:59]
	s_add_i32 m0, s60, 0x2000
	s_nop 0
	global_load_lds_dwordx4 v128, s[58:59]
	s_mov_b32 m0, s45
	s_nop 0
	global_load_lds_dwordx4 v134, s[100:101]
	s_mov_b32 m0, s46
	s_nop 0
	global_load_lds_dwordx4 v130, s[100:101]
	s_waitcnt vmcnt(8)
	s_waitcnt lgkmcnt(0)
	s_barrier
	s_setprio 1
	v_mfma_f32_16x16x32_bf16 v[60:63], v[148:151], v[180:183], v[60:63]
	v_mfma_f32_16x16x32_bf16 v[52:55], v[156:159], v[180:183], v[52:55]
	v_mfma_f32_16x16x32_bf16 v[44:47], v[148:151], v[200:203], v[44:47]
	v_mfma_f32_16x16x32_bf16 v[36:39], v[156:159], v[200:203], v[36:39]
	v_mfma_f32_16x16x32_bf16 v[28:31], v[148:151], v[208:211], v[28:31]
	v_mfma_f32_16x16x32_bf16 v[20:23], v[156:159], v[208:211], v[20:23]
	v_mfma_f32_16x16x32_bf16 v[12:15], v[148:151], v[216:219], v[12:15]
	v_mfma_f32_16x16x32_bf16 v[4:7], v[156:159], v[216:219], v[4:7]
	v_mfma_f32_16x16x32_bf16 v[60:63], v[152:155], v[184:187], v[60:63]
	v_mfma_f32_16x16x32_bf16 v[52:55], v[160:163], v[184:187], v[52:55]
	v_mfma_f32_16x16x32_bf16 v[44:47], v[152:155], v[204:207], v[44:47]
	v_mfma_f32_16x16x32_bf16 v[36:39], v[160:163], v[204:207], v[36:39]
	v_mfma_f32_16x16x32_bf16 v[28:31], v[152:155], v[212:215], v[28:31]
	v_mfma_f32_16x16x32_bf16 v[20:23], v[160:163], v[212:215], v[20:23]
	v_mfma_f32_16x16x32_bf16 v[12:15], v[152:155], v[226:229], v[12:15]
	v_mfma_f32_16x16x32_bf16 v[4:7], v[160:163], v[226:229], v[4:7]
	s_setprio 0
	s_setprio 1
	v_mfma_f32_16x16x32_bf16 v[56:59], v[164:167], v[180:183], v[56:59]
	v_mfma_f32_16x16x32_bf16 v[48:51], v[172:175], v[180:183], v[48:51]
	v_mfma_f32_16x16x32_bf16 v[40:43], v[164:167], v[200:203], v[40:43]
	v_mfma_f32_16x16x32_bf16 v[32:35], v[172:175], v[200:203], v[32:35]
	v_mfma_f32_16x16x32_bf16 v[24:27], v[164:167], v[208:211], v[24:27]
	v_mfma_f32_16x16x32_bf16 v[16:19], v[172:175], v[208:211], v[16:19]
	v_mfma_f32_16x16x32_bf16 v[8:11], v[164:167], v[216:219], v[8:11]
	v_mfma_f32_16x16x32_bf16 v[0:3], v[172:175], v[216:219], v[0:3]
	v_mfma_f32_16x16x32_bf16 v[56:59], v[168:171], v[184:187], v[56:59]
	v_mfma_f32_16x16x32_bf16 v[48:51], v[176:179], v[184:187], v[48:51]
	v_mfma_f32_16x16x32_bf16 v[40:43], v[168:171], v[204:207], v[40:43]
	v_mfma_f32_16x16x32_bf16 v[32:35], v[176:179], v[204:207], v[32:35]
	v_mfma_f32_16x16x32_bf16 v[24:27], v[168:171], v[212:215], v[24:27]
	v_mfma_f32_16x16x32_bf16 v[16:19], v[176:179], v[212:215], v[16:19]
	v_mfma_f32_16x16x32_bf16 v[8:11], v[168:171], v[226:229], v[8:11]
	v_mfma_f32_16x16x32_bf16 v[0:3], v[176:179], v[226:229], v[0:3]
	s_setprio 0
	s_barrier
; #define PG8_STAGE(bufoff, gbase, voff) do { _Pragma("unroll") for (int _i = 0; _i < 2; ++_i) \
;         __builtin_amdgcn_global_load_lds((const unsigned*)((const char*)(gbase) + (voff)[_i]), (PG8_LAS unsigned*)(lds + (bufoff) + ldsw + _i * 8192), 16, 0, 0); } while (0)
; #define PG8_LDA(dst, b, h) do { _Pragma("unroll") for (int m = 0; m < 4; ++m) _Pragma("unroll") for (int k = 0; k < 2; ++k) dst[m][k] = *(const PG8_LAS bf16x8*)(lds + PG8_SA(b, h) + aoff + m * 2048 + k * 1024); } while (0)
; #define PG8_LDB(dst, b, h) do { _Pragma("unroll") for (int n = 0; n < 2; ++n) _Pragma("unroll") for (int k = 0; k < 2; ++k) dst[n][k] = *(const PG8_LAS bf16x8*)(lds + PG8_SB(b, h) + boff + n * 2048 + k * 1024); } while (0)
; #define PG8_MMA(ai, bj, At, Bt) do { __builtin_amdgcn_s_setprio(1); _Pragma("unroll") for (int m = 0; m < 4; ++m) _Pragma("unroll") for (int n = 0; n < 2; ++n) _Pragma("unroll") for (int k = 0; k < 2; ++k) \
;         acc[ai][bj][m][n] = __builtin_amdgcn_mfma_f32_16x16x32_bf16(Bt[n][k], At[m][k], acc[ai][bj][m][n], 0, 0, 0); __builtin_amdgcn_s_setprio(0); } while (0)
; #define PG8_WAIT_V(n) asm volatile("s_waitcnt vmcnt(" #n ")" ::: "memory")
; #define PG8_WAIT_L(n) asm volatile("s_waitcnt lgkmcnt(" #n ")" ::: "memory")
; #define PG8_BAR __builtin_amdgcn_s_barrier()
; #define PG8_SCHED __builtin_amdgcn_sched_barrier(0)
; template <class Epi, class Sched, bool ALIGN_EPI = false, bool SP2 = false>
; __device__ __forceinline__ void gemm_phase(PG8_LAS unsigned char* lds, const Gemm g, const Sched& S, const Epi& E, int tid_in) {
;     ...
;             PG8_LDB(B0, 1, 0); PG8_LDB(B1, 1, 1); PG8_SCHED; PG8_LDA(At, 1, 0); PG8_STAGE(PG8_SA(0, 1), a2 + hstepA, voffA);
;             PG8_WAIT_V(8); PG8_WAIT_L(0); PG8_BAR; PG8_MMA(0, 0, At, B0); PG8_MMA(0, 1, At, B1); PG8_BAR; PG8_SCHED;
;             PG8_LDA(At, 1, 1); PG8_STAGE(PG8_SB(1, 0), b3, voffB); PG8_STAGE(PG8_SB(1, 1), b3 + hstep, voffB); PG8_STAGE(PG8_SA(1, 0), a3, voffA);
;             PG8_WAIT_V(8); PG8_WAIT_L(0); PG8_BAR; PG8_MMA(1, 0, At, B0); PG8_MMA(1, 1, At, B1); PG8_BAR; PG8_SCHED;
	s_add_i32 s58, 0, 0x18000
	v_add_u32_e32 v142, s58, v145
	s_add_i32 s59, 0, 0x1c000
	ds_read_b128 v[148:151], v142
	ds_read_b128 v[152:155], v142 offset:1024
	ds_read_b128 v[156:159], v142 offset:2048
	ds_read_b128 v[160:163], v142 offset:3072
	v_add_u32_e32 v142, s59, v145
	ds_read_b128 v[164:167], v142
	ds_read_b128 v[168:171], v142 offset:1024
	ds_read_b128 v[172:175], v142 offset:2048
	ds_read_b128 v[176:179], v142 offset:3072
	s_add_u32 s14, s14, 0x40000
	s_addc_u32 s15, s15, 0
	s_mov_b32 m0, s47
	ds_read_b128 v[180:183], v146 offset:32768
	ds_read_b128 v[184:187], v146 offset:33792
	ds_read_b128 v[200:203], v146 offset:34816
	ds_read_b128 v[204:207], v146 offset:35840
	ds_read_b128 v[208:211], v146 offset:36864
	ds_read_b128 v[212:215], v146 offset:37888
	ds_read_b128 v[216:219], v146 offset:38912
	ds_read_b128 v[226:229], v146 offset:39936
	global_load_lds_dwordx4 v134, s[14:15]
	s_mov_b32 m0, s49
	s_nop 0
	global_load_lds_dwordx4 v130, s[14:15]
	s_waitcnt vmcnt(8)
	s_waitcnt lgkmcnt(0)
	s_barrier
	s_setprio 1
	v_mfma_f32_16x16x32_bf16 v[124:127], v[148:151], v[180:183], v[124:127]
	v_mfma_f32_16x16x32_bf16 v[116:119], v[156:159], v[180:183], v[116:119]
	v_mfma_f32_16x16x32_bf16 v[108:111], v[148:151], v[200:203], v[108:111]
	v_mfma_f32_16x16x32_bf16 v[100:103], v[156:159], v[200:203], v[100:103]
	v_mfma_f32_16x16x32_bf16 v[92:95], v[148:151], v[208:211], v[92:95]
	v_mfma_f32_16x16x32_bf16 v[84:87], v[156:159], v[208:211], v[84:87]
	v_mfma_f32_16x16x32_bf16 v[76:79], v[148:151], v[216:219], v[76:79]
	v_mfma_f32_16x16x32_bf16 v[68:71], v[156:159], v[216:219], v[68:71]
	v_mfma_f32_16x16x32_bf16 v[124:127], v[152:155], v[184:187], v[124:127]
	v_mfma_f32_16x16x32_bf16 v[116:119], v[160:163], v[184:187], v[116:119]
	v_mfma_f32_16x16x32_bf16 v[108:111], v[152:155], v[204:207], v[108:111]
	v_mfma_f32_16x16x32_bf16 v[100:103], v[160:163], v[204:207], v[100:103]
	v_mfma_f32_16x16x32_bf16 v[92:95], v[152:155], v[212:215], v[92:95]
	v_mfma_f32_16x16x32_bf16 v[84:87], v[160:163], v[212:215], v[84:87]
	v_mfma_f32_16x16x32_bf16 v[76:79], v[152:155], v[226:229], v[76:79]
	v_mfma_f32_16x16x32_bf16 v[68:71], v[160:163], v[226:229], v[68:71]
	s_setprio 0
	s_setprio 1
	v_mfma_f32_16x16x32_bf16 v[120:123], v[164:167], v[180:183], v[120:123]
	v_mfma_f32_16x16x32_bf16 v[112:115], v[172:175], v[180:183], v[112:115]
	v_mfma_f32_16x16x32_bf16 v[104:107], v[164:167], v[200:203], v[104:107]
	v_mfma_f32_16x16x32_bf16 v[96:99], v[172:175], v[200:203], v[96:99]
	v_mfma_f32_16x16x32_bf16 v[88:91], v[164:167], v[208:211], v[88:91]
	v_mfma_f32_16x16x32_bf16 v[80:83], v[172:175], v[208:211], v[80:83]
	v_mfma_f32_16x16x32_bf16 v[72:75], v[164:167], v[216:219], v[72:75]
	v_mfma_f32_16x16x32_bf16 v[64:67], v[172:175], v[216:219], v[64:67]
	v_mfma_f32_16x16x32_bf16 v[120:123], v[168:171], v[184:187], v[120:123]
	v_mfma_f32_16x16x32_bf16 v[112:115], v[176:179], v[184:187], v[112:115]
	v_mfma_f32_16x16x32_bf16 v[104:107], v[168:171], v[204:207], v[104:107]
	v_mfma_f32_16x16x32_bf16 v[96:99], v[176:179], v[204:207], v[96:99]
	v_mfma_f32_16x16x32_bf16 v[88:91], v[168:171], v[212:215], v[88:91]
	v_mfma_f32_16x16x32_bf16 v[80:83], v[176:179], v[212:215], v[80:83]
	v_mfma_f32_16x16x32_bf16 v[72:75], v[168:171], v[226:229], v[72:75]
	v_mfma_f32_16x16x32_bf16 v[64:67], v[176:179], v[226:229], v[64:67]
	s_setprio 0
	s_barrier
	s_add_i32 s14, s58, s44
	s_mov_b32 m0, s14
	ds_read_b128 v[180:183], v146 offset:49152
	ds_read_b128 v[184:187], v146 offset:50176
	ds_read_b128 v[200:203], v146 offset:51200
	ds_read_b128 v[204:207], v146 offset:52224
	ds_read_b128 v[208:211], v146 offset:53248
	ds_read_b128 v[212:215], v146 offset:54272
	ds_read_b128 v[216:219], v146 offset:55296
	ds_read_b128 v[226:229], v146 offset:56320
	s_add_u32 s12, s12, 0x80
	s_addc_u32 s13, s13, 0
	global_load_lds_dwordx4 v132, s[12:13]
	s_add_i32 m0, s14, 0x2000
	s_nop 0
	global_load_lds_dwordx4 v128, s[12:13]
	s_add_u32 s12, s12, 0x40000
	s_addc_u32 s13, s13, 0
	s_add_i32 s14, s59, s44
	s_mov_b32 m0, s14
	s_nop 0
	global_load_lds_dwordx4 v132, s[12:13]
	s_add_i32 m0, s14, 0x2000
	s_nop 0
	global_load_lds_dwordx4 v128, s[12:13]
	s_mov_b32 m0, s50
	s_nop 0
	s_add_u32 s100, s100, 0x80
	s_addc_u32 s101, s101, 0
	global_load_lds_dwordx4 v134, s[100:101]
	s_mov_b32 m0, s51
	s_nop 0
	global_load_lds_dwordx4 v130, s[100:101]
	s_waitcnt vmcnt(8)
	s_waitcnt lgkmcnt(0)
	s_barrier
	s_setprio 1
	v_mfma_f32_16x16x32_bf16 v[60:63], v[148:151], v[180:183], v[60:63]
	v_mfma_f32_16x16x32_bf16 v[52:55], v[156:159], v[180:183], v[52:55]
	v_mfma_f32_16x16x32_bf16 v[44:47], v[148:151], v[200:203], v[44:47]
	v_mfma_f32_16x16x32_bf16 v[36:39], v[156:159], v[200:203], v[36:39]
	v_mfma_f32_16x16x32_bf16 v[28:31], v[148:151], v[208:211], v[28:31]
	v_mfma_f32_16x16x32_bf16 v[20:23], v[156:159], v[208:211], v[20:23]
	v_mfma_f32_16x16x32_bf16 v[12:15], v[148:151], v[216:219], v[12:15]
	v_mfma_f32_16x16x32_bf16 v[4:7], v[156:159], v[216:219], v[4:7]
	v_mfma_f32_16x16x32_bf16 v[60:63], v[152:155], v[184:187], v[60:63]
	v_mfma_f32_16x16x32_bf16 v[52:55], v[160:163], v[184:187], v[52:55]
	v_mfma_f32_16x16x32_bf16 v[44:47], v[152:155], v[204:207], v[44:47]
	v_mfma_f32_16x16x32_bf16 v[36:39], v[160:163], v[204:207], v[36:39]
	v_mfma_f32_16x16x32_bf16 v[28:31], v[152:155], v[212:215], v[28:31]
	v_mfma_f32_16x16x32_bf16 v[20:23], v[160:163], v[212:215], v[20:23]
	v_mfma_f32_16x16x32_bf16 v[12:15], v[152:155], v[226:229], v[12:15]
	v_mfma_f32_16x16x32_bf16 v[4:7], v[160:163], v[226:229], v[4:7]
	s_setprio 0
	s_setprio 1
	v_mfma_f32_16x16x32_bf16 v[56:59], v[164:167], v[180:183], v[56:59]
	v_mfma_f32_16x16x32_bf16 v[48:51], v[172:175], v[180:183], v[48:51]
	v_mfma_f32_16x16x32_bf16 v[40:43], v[164:167], v[200:203], v[40:43]
	v_mfma_f32_16x16x32_bf16 v[32:35], v[172:175], v[200:203], v[32:35]
	v_mfma_f32_16x16x32_bf16 v[24:27], v[164:167], v[208:211], v[24:27]
	v_mfma_f32_16x16x32_bf16 v[16:19], v[172:175], v[208:211], v[16:19]
	v_mfma_f32_16x16x32_bf16 v[8:11], v[164:167], v[216:219], v[8:11]
	v_mfma_f32_16x16x32_bf16 v[0:3], v[172:175], v[216:219], v[0:3]
	v_mfma_f32_16x16x32_bf16 v[56:59], v[168:171], v[184:187], v[56:59]
	v_mfma_f32_16x16x32_bf16 v[48:51], v[176:179], v[184:187], v[48:51]
	v_mfma_f32_16x16x32_bf16 v[40:43], v[168:171], v[204:207], v[40:43]
	v_mfma_f32_16x16x32_bf16 v[32:35], v[176:179], v[204:207], v[32:35]
	v_mfma_f32_16x16x32_bf16 v[24:27], v[168:171], v[212:215], v[24:27]
	v_mfma_f32_16x16x32_bf16 v[16:19], v[176:179], v[212:215], v[16:19]
	v_mfma_f32_16x16x32_bf16 v[8:11], v[168:171], v[226:229], v[8:11]
	v_mfma_f32_16x16x32_bf16 v[0:3], v[176:179], v[226:229], v[0:3]
	s_setprio 0
	s_barrier
	s_add_i32 s57, s57, 2
	s_add_u32 s55, s55, 0x100
	s_addc_u32 s56, s56, 0
	s_add_u32 s2, s2, 0x100
	s_addc_u32 s3, s3, 0
	s_cmp_gt_u32 s57, 13
	s_cbranch_scc0 .LBB0_1385
	s_and_b64 vcc, exec, s[10:11]
	s_cbranch_vccz .LBB0_1388
	s_barrier

; #define PG8_STAGE(bufoff, gbase, voff) do { _Pragma("unroll") for (int _i = 0; _i < 2; ++_i) \
;         __builtin_amdgcn_global_load_lds((const unsigned*)((const char*)(gbase) + (voff)[_i]), (PG8_LAS unsigned*)(lds + (bufoff) + ldsw + _i * 8192), 16, 0, 0); } while (0)
; #define PG8_LDA(dst, b, h) do { _Pragma("unroll") for (int m = 0; m < 4; ++m) _Pragma("unroll") for (int k = 0; k < 2; ++k) dst[m][k] = *(const PG8_LAS bf16x8*)(lds + PG8_SA(b, h) + aoff + m * 2048 + k * 1024); } while (0)
; #define PG8_LDB(dst, b, h) do { _Pragma("unroll") for (int n = 0; n < 2; ++n) _Pragma("unroll") for (int k = 0; k < 2; ++k) dst[n][k] = *(const PG8_LAS bf16x8*)(lds + PG8_SB(b, h) + boff + n * 2048 + k * 1024); } while (0)
; #define PG8_MMA(ai, bj, At, Bt) do { __builtin_amdgcn_s_setprio(1); _Pragma("unroll") for (int m = 0; m < 4; ++m) _Pragma("unroll") for (int n = 0; n < 2; ++n) _Pragma("unroll") for (int k = 0; k < 2; ++k) \
;         acc[ai][bj][m][n] = __builtin_amdgcn_mfma_f32_16x16x32_bf16(Bt[n][k], At[m][k], acc[ai][bj][m][n], 0, 0, 0); __builtin_amdgcn_s_setprio(0); } while (0)
; #define PG8_WAIT_V(n) asm volatile("s_waitcnt vmcnt(" #n ")" ::: "memory")
; #define PG8_WAIT_L(n) asm volatile("s_waitcnt lgkmcnt(" #n ")" ::: "memory")
; #define PG8_BAR __builtin_amdgcn_s_barrier()
; #define PG8_SCHED __builtin_amdgcn_sched_barrier(0)
; template <class Epi, class Sched, bool ALIGN_EPI = false, bool SP2 = false>
; __device__ __forceinline__ void gemm_phase(PG8_LAS unsigned char* lds, const Gemm g, const Sched& S, const Epi& E, int tid_in) {
;     ...
;             const bool last = (t == nt - 2);
;             const char* a1 = cA + (size_t)(t + 1) * kstep;
;             const char* a2 = last ? nA : cA + (size_t)(t + 2) * kstep; const char* b2 = last ? nB : cB + (size_t)(t + 2) * kstep;
;             const char* a3 = a2 + kstep; const char* b3 = b2 + kstep;
;             if (last && has_next) S.a_ready(nxt);
;             if constexpr (SP2) {
;             PG8_LDB(B0, 0, 0); PG8_LDB(B1, 0, 1); PG8_SCHED; PG8_LDA(At, 0, 0); PG8_STAGE(PG8_SA(1, 1), a1 + hstepA, voffA);
;             PG8_WAIT_V(8); PG8_WAIT_L(0); PG8_BAR; PG8_MMA(0, 0, At, B0); PG8_MMA(0, 1, At, B1); PG8_BAR; PG8_SCHED;
;             PG8_LDA(At, 0, 1); PG8_STAGE(PG8_SB(0, 0), b2, voffB); PG8_STAGE(PG8_SB(0, 1), b2 + hstep, voffB); PG8_STAGE(PG8_SA(0, 0), a2, voffA);
.LBB0_1479:
	s_add_u32 s14, s12, 0x100
	s_addc_u32 s15, s13, 0
	s_add_i32 s56, 0, 0x10000
	s_cmp_eq_u32 s55, 40
	s_cselect_b32 s25, s11, s15
	s_cselect_b32 s24, s10, s14
	s_cselect_b32 s21, s19, s45
	s_cselect_b32 s20, s18, s44
	s_add_i32 s57, 0, 0x14000
	v_add_u32_e32 v124, s56, v226
	v_add_u32_e32 v140, s57, v226
	ds_read_b128 v[112:115], v124
	ds_read_b128 v[116:119], v124 offset:1024
	ds_read_b128 v[120:123], v124 offset:2048
	ds_read_b128 v[124:127], v124 offset:3072
	ds_read_b128 v[128:131], v140
	ds_read_b128 v[132:135], v140 offset:1024
	ds_read_b128 v[136:139], v140 offset:2048
	ds_read_b128 v[140:143], v140 offset:3072
	s_add_i32 m0, s31, 0xc000
	ds_read_b128 v[144:147], v227
	ds_read_b128 v[148:151], v227 offset:1024
	ds_read_b128 v[152:155], v227 offset:2048
	ds_read_b128 v[156:159], v227 offset:3072
	ds_read_b128 v[176:179], v227 offset:4096
	ds_read_b128 v[180:183], v227 offset:5120
	ds_read_b128 v[208:211], v227 offset:6144
	ds_read_b128 v[212:215], v227 offset:7168
	global_load_lds_dwordx4 v206, s[12:13]
	s_add_i32 m0, s31, 0xe000
	s_nop 0
	global_load_lds_dwordx4 v204, s[12:13]
	s_waitcnt vmcnt(8)
	s_waitcnt lgkmcnt(0)
	s_barrier
	s_setprio 1
	v_mfma_f32_16x16x32_bf16 v[172:175], v[112:115], v[144:147], v[172:175]
	v_mfma_f32_16x16x32_bf16 v[168:171], v[120:123], v[144:147], v[168:171]
	v_mfma_f32_16x16x32_bf16 v[108:111], v[112:115], v[152:155], v[108:111]
	v_mfma_f32_16x16x32_bf16 v[104:107], v[120:123], v[152:155], v[104:107]
	v_mfma_f32_16x16x32_bf16 v[92:95], v[112:115], v[176:179], v[92:95]
	v_mfma_f32_16x16x32_bf16 v[88:91], v[120:123], v[176:179], v[88:91]
	v_mfma_f32_16x16x32_bf16 v[76:79], v[112:115], v[208:211], v[76:79]
	v_mfma_f32_16x16x32_bf16 v[72:75], v[120:123], v[208:211], v[72:75]
	v_mfma_f32_16x16x32_bf16 v[172:175], v[116:119], v[148:151], v[172:175]
	v_mfma_f32_16x16x32_bf16 v[168:171], v[124:127], v[148:151], v[168:171]
	v_mfma_f32_16x16x32_bf16 v[108:111], v[116:119], v[156:159], v[108:111]
	v_mfma_f32_16x16x32_bf16 v[104:107], v[124:127], v[156:159], v[104:107]
	v_mfma_f32_16x16x32_bf16 v[92:95], v[116:119], v[180:183], v[92:95]
	v_mfma_f32_16x16x32_bf16 v[88:91], v[124:127], v[180:183], v[88:91]
	v_mfma_f32_16x16x32_bf16 v[76:79], v[116:119], v[212:215], v[76:79]
	v_mfma_f32_16x16x32_bf16 v[72:75], v[124:127], v[212:215], v[72:75]
	s_setprio 0
	s_setprio 1
	v_mfma_f32_16x16x32_bf16 v[164:167], v[128:131], v[144:147], v[164:167]
	v_mfma_f32_16x16x32_bf16 v[100:103], v[128:131], v[152:155], v[100:103]
	v_mfma_f32_16x16x32_bf16 v[96:99], v[136:139], v[152:155], v[96:99]
	v_mfma_f32_16x16x32_bf16 v[84:87], v[128:131], v[176:179], v[84:87]
	v_mfma_f32_16x16x32_bf16 v[80:83], v[136:139], v[176:179], v[80:83]
	v_mfma_f32_16x16x32_bf16 v[68:71], v[128:131], v[208:211], v[68:71]
	v_mfma_f32_16x16x32_bf16 v[64:67], v[136:139], v[208:211], v[64:67]
	v_mfma_f32_16x16x32_bf16 v[164:167], v[132:135], v[148:151], v[164:167]
	v_mfma_f32_16x16x32_bf16 v[144:147], v[136:139], v[144:147], v[160:163]
	v_mfma_f32_16x16x32_bf16 v[100:103], v[132:135], v[156:159], v[100:103]
	v_mfma_f32_16x16x32_bf16 v[96:99], v[140:143], v[156:159], v[96:99]
	v_mfma_f32_16x16x32_bf16 v[84:87], v[132:135], v[180:183], v[84:87]
	v_mfma_f32_16x16x32_bf16 v[80:83], v[140:143], v[180:183], v[80:83]
	v_mfma_f32_16x16x32_bf16 v[68:71], v[132:135], v[212:215], v[68:71]
	v_mfma_f32_16x16x32_bf16 v[64:67], v[140:143], v[212:215], v[64:67]
	v_mfma_f32_16x16x32_bf16 v[144:147], v[140:143], v[148:151], v[144:147]
	s_setprio 0
	s_barrier
	s_add_i32 s12, s56, s30
	s_mov_b64 s[100:101], s[20:21]
	s_mov_b32 m0, s12
	ds_read_b128 v[148:151], v227 offset:16384
	ds_read_b128 v[152:155], v227 offset:17408
	ds_read_b128 v[156:159], v227 offset:18432
	ds_read_b128 v[160:163], v227 offset:19456
	ds_read_b128 v[176:179], v227 offset:20480
	ds_read_b128 v[180:183], v227 offset:21504
	ds_read_b128 v[208:211], v227 offset:22528
	ds_read_b128 v[212:215], v227 offset:23552
	global_load_lds_dwordx4 v190, s[100:101]
	s_add_i32 m0, s12, 0x2000
	s_add_u32 s12, s20, 0xb0000
	s_addc_u32 s13, s21, 0
	s_add_i32 s56, s57, s30
	global_load_lds_dwordx4 v184, s[100:101]
	s_mov_b32 m0, s56
	v_lshl_add_u64 v[232:233], s[24:25], 0, v[188:189]
	global_load_lds_dwordx4 v190, s[12:13]
	s_add_i32 m0, s56, 0x2000
	v_lshl_add_u64 v[234:235], s[24:25], 0, v[186:187]
	global_load_lds_dwordx4 v184, s[12:13]
	s_mov_b32 m0, s31
	s_nop 0
	global_load_lds_dwordx4 v[232:233], off
	s_mov_b32 m0, s34
	s_nop 0
	global_load_lds_dwordx4 v[234:235], off
	s_waitcnt vmcnt(8)
	s_waitcnt lgkmcnt(0)
	s_barrier
; #define PG8_STAGE(bufoff, gbase, voff) do { _Pragma("unroll") for (int _i = 0; _i < 2; ++_i) \
;         __builtin_amdgcn_global_load_lds((const unsigned*)((const char*)(gbase) + (voff)[_i]), (PG8_LAS unsigned*)(lds + (bufoff) + ldsw + _i * 8192), 16, 0, 0); } while (0)
; #define PG8_LDA(dst, b, h) do { _Pragma("unroll") for (int m = 0; m < 4; ++m) _Pragma("unroll") for (int k = 0; k < 2; ++k) dst[m][k] = *(const PG8_LAS bf16x8*)(lds + PG8_SA(b, h) + aoff + m * 2048 + k * 1024); } while (0)
; #define PG8_LDB(dst, b, h) do { _Pragma("unroll") for (int n = 0; n < 2; ++n) _Pragma("unroll") for (int k = 0; k < 2; ++k) dst[n][k] = *(const PG8_LAS bf16x8*)(lds + PG8_SB(b, h) + boff + n * 2048 + k * 1024); } while (0)
; #define PG8_MMA(ai, bj, At, Bt) do { __builtin_amdgcn_s_setprio(1); _Pragma("unroll") for (int m = 0; m < 4; ++m) _Pragma("unroll") for (int n = 0; n < 2; ++n) _Pragma("unroll") for (int k = 0; k < 2; ++k) \
;         acc[ai][bj][m][n] = __builtin_amdgcn_mfma_f32_16x16x32_bf16(Bt[n][k], At[m][k], acc[ai][bj][m][n], 0, 0, 0); __builtin_amdgcn_s_setprio(0); } while (0)
; #define PG8_WAIT_V(n) asm volatile("s_waitcnt vmcnt(" #n ")" ::: "memory")
; #define PG8_WAIT_L(n) asm volatile("s_waitcnt lgkmcnt(" #n ")" ::: "memory")
; #define PG8_BAR __builtin_amdgcn_s_barrier()
; #define PG8_SCHED __builtin_amdgcn_sched_barrier(0)
; template <class Epi, class Sched, bool ALIGN_EPI = false, bool SP2 = false>
; __device__ __forceinline__ void gemm_phase(PG8_LAS unsigned char* lds, const Gemm g, const Sched& S, const Epi& E, int tid_in) {
;     ...
;             PG8_WAIT_V(8); PG8_WAIT_L(0); PG8_BAR; PG8_MMA(1, 0, At, B0); PG8_MMA(1, 1, At, B1); PG8_BAR; PG8_SCHED;
;             PG8_LDB(B0, 1, 0); PG8_LDB(B1, 1, 1); PG8_SCHED; PG8_LDA(At, 1, 0); PG8_STAGE(PG8_SA(0, 1), a2 + hstepA, voffA);
;             PG8_WAIT_V(8); PG8_WAIT_L(0); PG8_BAR; PG8_MMA(0, 0, At, B0); PG8_MMA(0, 1, At, B1); PG8_BAR; PG8_SCHED;
	s_setprio 1
	v_mfma_f32_16x16x32_bf16 v[60:63], v[112:115], v[148:151], v[60:63]
	v_mfma_f32_16x16x32_bf16 v[56:59], v[120:123], v[148:151], v[56:59]
	v_mfma_f32_16x16x32_bf16 v[44:47], v[112:115], v[156:159], v[44:47]
	v_mfma_f32_16x16x32_bf16 v[40:43], v[120:123], v[156:159], v[40:43]
	v_mfma_f32_16x16x32_bf16 v[28:31], v[112:115], v[176:179], v[28:31]
	v_mfma_f32_16x16x32_bf16 v[24:27], v[120:123], v[176:179], v[24:27]
	v_mfma_f32_16x16x32_bf16 v[12:15], v[112:115], v[208:211], v[12:15]
	v_mfma_f32_16x16x32_bf16 v[8:11], v[120:123], v[208:211], v[8:11]
	v_mfma_f32_16x16x32_bf16 v[60:63], v[116:119], v[152:155], v[60:63]
	v_mfma_f32_16x16x32_bf16 v[56:59], v[124:127], v[152:155], v[56:59]
	v_mfma_f32_16x16x32_bf16 v[44:47], v[116:119], v[160:163], v[44:47]
	v_mfma_f32_16x16x32_bf16 v[40:43], v[124:127], v[160:163], v[40:43]
	v_mfma_f32_16x16x32_bf16 v[28:31], v[116:119], v[180:183], v[28:31]
	v_mfma_f32_16x16x32_bf16 v[24:27], v[124:127], v[180:183], v[24:27]
	v_mfma_f32_16x16x32_bf16 v[12:15], v[116:119], v[212:215], v[12:15]
	v_mfma_f32_16x16x32_bf16 v[8:11], v[124:127], v[212:215], v[8:11]
	s_setprio 0
	s_setprio 1
	v_mfma_f32_16x16x32_bf16 v[52:55], v[128:131], v[148:151], v[52:55]
	v_mfma_f32_16x16x32_bf16 v[48:51], v[136:139], v[148:151], v[48:51]
	v_mfma_f32_16x16x32_bf16 v[36:39], v[128:131], v[156:159], v[36:39]
	v_mfma_f32_16x16x32_bf16 v[32:35], v[136:139], v[156:159], v[32:35]
	v_mfma_f32_16x16x32_bf16 v[20:23], v[128:131], v[176:179], v[20:23]
	v_mfma_f32_16x16x32_bf16 v[16:19], v[136:139], v[176:179], v[16:19]
	v_mfma_f32_16x16x32_bf16 v[4:7], v[128:131], v[208:211], v[4:7]
	v_mfma_f32_16x16x32_bf16 v[0:3], v[136:139], v[208:211], v[0:3]
	v_mfma_f32_16x16x32_bf16 v[52:55], v[132:135], v[152:155], v[52:55]
	v_mfma_f32_16x16x32_bf16 v[48:51], v[140:143], v[152:155], v[48:51]
	v_mfma_f32_16x16x32_bf16 v[36:39], v[132:135], v[160:163], v[36:39]
	v_mfma_f32_16x16x32_bf16 v[32:35], v[140:143], v[160:163], v[32:35]
	v_mfma_f32_16x16x32_bf16 v[20:23], v[132:135], v[180:183], v[20:23]
	v_mfma_f32_16x16x32_bf16 v[16:19], v[140:143], v[180:183], v[16:19]
	v_mfma_f32_16x16x32_bf16 v[4:7], v[132:135], v[212:215], v[4:7]
	v_mfma_f32_16x16x32_bf16 v[0:3], v[140:143], v[212:215], v[0:3]
	s_setprio 0
	s_barrier
	s_add_i32 s56, 0, 0x18000
	s_add_i32 s57, 0, 0x1c000
	v_add_u32_e32 v124, s56, v226
	v_add_u32_e32 v140, s57, v226
	ds_read_b128 v[112:115], v124
	ds_read_b128 v[116:119], v124 offset:1024
	ds_read_b128 v[120:123], v124 offset:2048
	ds_read_b128 v[124:127], v124 offset:3072
	ds_read_b128 v[128:131], v140
	ds_read_b128 v[132:135], v140 offset:1024
	ds_read_b128 v[136:139], v140 offset:2048
	ds_read_b128 v[140:143], v140 offset:3072
	s_add_u32 s12, s24, 0xb0000
	s_addc_u32 s13, s25, 0
	s_mov_b32 m0, s35
	ds_read_b128 v[148:151], v227 offset:32768
	ds_read_b128 v[152:155], v227 offset:33792
	ds_read_b128 v[156:159], v227 offset:34816
	ds_read_b128 v[176:179], v227 offset:35840
	ds_read_b128 v[180:183], v227 offset:36864
	ds_read_b128 v[208:211], v227 offset:37888
	ds_read_b128 v[212:215], v227 offset:38912
	ds_read_b128 v[216:219], v227 offset:39936
	global_load_lds_dwordx4 v188, s[12:13]
	s_mov_b32 m0, s46
	s_nop 0
	global_load_lds_dwordx4 v186, s[12:13]
	s_waitcnt vmcnt(8)
	s_waitcnt lgkmcnt(0)
	s_barrier
	s_setprio 1
	v_mfma_f32_16x16x32_bf16 v[160:163], v[112:115], v[148:151], v[172:175]
	v_mfma_f32_16x16x32_bf16 v[172:175], v[116:119], v[152:155], v[160:163]
	v_mfma_f32_16x16x32_bf16 v[160:163], v[120:123], v[148:151], v[168:171]
	v_mfma_f32_16x16x32_bf16 v[108:111], v[112:115], v[156:159], v[108:111]
	v_mfma_f32_16x16x32_bf16 v[104:107], v[120:123], v[156:159], v[104:107]
	v_mfma_f32_16x16x32_bf16 v[92:95], v[112:115], v[180:183], v[92:95]
	v_mfma_f32_16x16x32_bf16 v[88:91], v[120:123], v[180:183], v[88:91]
	v_mfma_f32_16x16x32_bf16 v[76:79], v[112:115], v[212:215], v[76:79]
	v_mfma_f32_16x16x32_bf16 v[72:75], v[120:123], v[212:215], v[72:75]
	v_mfma_f32_16x16x32_bf16 v[168:171], v[124:127], v[152:155], v[160:163]
	v_mfma_f32_16x16x32_bf16 v[108:111], v[116:119], v[176:179], v[108:111]
	v_mfma_f32_16x16x32_bf16 v[104:107], v[124:127], v[176:179], v[104:107]
	v_mfma_f32_16x16x32_bf16 v[92:95], v[116:119], v[208:211], v[92:95]
	v_mfma_f32_16x16x32_bf16 v[88:91], v[124:127], v[208:211], v[88:91]
	v_mfma_f32_16x16x32_bf16 v[76:79], v[116:119], v[216:219], v[76:79]
	v_mfma_f32_16x16x32_bf16 v[72:75], v[124:127], v[216:219], v[72:75]
	s_setprio 0
	s_setprio 1
	v_mfma_f32_16x16x32_bf16 v[160:163], v[128:131], v[148:151], v[164:167]
	v_mfma_f32_16x16x32_bf16 v[144:147], v[136:139], v[148:151], v[144:147]
	v_mfma_f32_16x16x32_bf16 v[100:103], v[128:131], v[156:159], v[100:103]
	v_mfma_f32_16x16x32_bf16 v[96:99], v[136:139], v[156:159], v[96:99]
	v_mfma_f32_16x16x32_bf16 v[84:87], v[128:131], v[180:183], v[84:87]
	v_mfma_f32_16x16x32_bf16 v[80:83], v[136:139], v[180:183], v[80:83]
	v_mfma_f32_16x16x32_bf16 v[68:71], v[128:131], v[212:215], v[68:71]
	v_mfma_f32_16x16x32_bf16 v[64:67], v[136:139], v[212:215], v[64:67]
	v_mfma_f32_16x16x32_bf16 v[164:167], v[132:135], v[152:155], v[160:163]
	v_mfma_f32_16x16x32_bf16 v[160:163], v[140:143], v[152:155], v[144:147]
	v_mfma_f32_16x16x32_bf16 v[100:103], v[132:135], v[176:179], v[100:103]
	v_mfma_f32_16x16x32_bf16 v[96:99], v[140:143], v[176:179], v[96:99]
	v_mfma_f32_16x16x32_bf16 v[84:87], v[132:135], v[208:211], v[84:87]
	v_mfma_f32_16x16x32_bf16 v[80:83], v[140:143], v[208:211], v[80:83]
	v_mfma_f32_16x16x32_bf16 v[68:71], v[132:135], v[216:219], v[68:71]
	v_mfma_f32_16x16x32_bf16 v[64:67], v[140:143], v[216:219], v[64:67]
	s_setprio 0
	s_barrier
; #define PG8_STAGE(bufoff, gbase, voff) do { _Pragma("unroll") for (int _i = 0; _i < 2; ++_i) \
;         __builtin_amdgcn_global_load_lds((const unsigned*)((const char*)(gbase) + (voff)[_i]), (PG8_LAS unsigned*)(lds + (bufoff) + ldsw + _i * 8192), 16, 0, 0); } while (0)
; #define PG8_LDA(dst, b, h) do { _Pragma("unroll") for (int m = 0; m < 4; ++m) _Pragma("unroll") for (int k = 0; k < 2; ++k) dst[m][k] = *(const PG8_LAS bf16x8*)(lds + PG8_SA(b, h) + aoff + m * 2048 + k * 1024); } while (0)
; #define PG8_MMA(ai, bj, At, Bt) do { __builtin_amdgcn_s_setprio(1); _Pragma("unroll") for (int m = 0; m < 4; ++m) _Pragma("unroll") for (int n = 0; n < 2; ++n) _Pragma("unroll") for (int k = 0; k < 2; ++k) \
;         acc[ai][bj][m][n] = __builtin_amdgcn_mfma_f32_16x16x32_bf16(Bt[n][k], At[m][k], acc[ai][bj][m][n], 0, 0, 0); __builtin_amdgcn_s_setprio(0); } while (0)
; #define PG8_WAIT_V(n) asm volatile("s_waitcnt vmcnt(" #n ")" ::: "memory")
; #define PG8_WAIT_L(n) asm volatile("s_waitcnt lgkmcnt(" #n ")" ::: "memory")
; #define PG8_BAR __builtin_amdgcn_s_barrier()
; #define PG8_SCHED __builtin_amdgcn_sched_barrier(0)
; template <class Epi, class Sched, bool ALIGN_EPI = false, bool SP2 = false>
; __device__ __forceinline__ void gemm_phase(PG8_LAS unsigned char* lds, const Gemm g, const Sched& S, const Epi& E, int tid_in) {
;     ...
;             PG8_LDA(At, 1, 1); PG8_STAGE(PG8_SB(1, 0), b3, voffB); PG8_STAGE(PG8_SB(1, 1), b3 + hstep, voffB); PG8_STAGE(PG8_SA(1, 0), a3, voffA);
;             PG8_WAIT_V(8); PG8_WAIT_L(0); PG8_BAR; PG8_MMA(1, 0, At, B0); PG8_MMA(1, 1, At, B1); PG8_BAR; PG8_SCHED;
	s_add_i32 s12, s56, s30
	s_mov_b32 m0, s12
	ds_read_b128 v[144:147], v227 offset:49152
	ds_read_b128 v[148:151], v227 offset:50176
	ds_read_b128 v[152:155], v227 offset:51200
	ds_read_b128 v[156:159], v227 offset:52224
	ds_read_b128 v[176:179], v227 offset:53248
	ds_read_b128 v[180:183], v227 offset:54272
	ds_read_b128 v[208:211], v227 offset:55296
	ds_read_b128 v[212:215], v227 offset:56320
	s_add_u32 s100, s100, 0x80
	s_addc_u32 s101, s101, 0
	global_load_lds_dwordx4 v190, s[100:101]
	s_add_i32 m0, s12, 0x2000
	s_add_u32 s12, s20, 0xb0080
	s_addc_u32 s13, s21, 0
	s_add_i32 s20, s57, s30
	global_load_lds_dwordx4 v184, s[100:101]
	s_mov_b32 m0, s20
	s_nop 0
	global_load_lds_dwordx4 v190, s[12:13]
	s_add_i32 m0, s20, 0x2000
	s_nop 0
	global_load_lds_dwordx4 v184, s[12:13]
	v_lshl_add_u64 v[216:217], v[232:233], 0, s[0:1]
	s_mov_b32 m0, s49
	s_nop 0
	global_load_lds_dwordx4 v[216:217], off
	v_lshl_add_u64 v[216:217], v[234:235], 0, s[0:1]
	s_mov_b32 m0, s50
	s_nop 0
	global_load_lds_dwordx4 v[216:217], off
	s_waitcnt vmcnt(8)
	s_waitcnt lgkmcnt(0)
	s_barrier
	s_setprio 1
	v_mfma_f32_16x16x32_bf16 v[60:63], v[112:115], v[144:147], v[60:63]
	v_mfma_f32_16x16x32_bf16 v[56:59], v[120:123], v[144:147], v[56:59]
	v_mfma_f32_16x16x32_bf16 v[44:47], v[112:115], v[152:155], v[44:47]
	v_mfma_f32_16x16x32_bf16 v[40:43], v[120:123], v[152:155], v[40:43]
	v_mfma_f32_16x16x32_bf16 v[28:31], v[112:115], v[176:179], v[28:31]
	v_mfma_f32_16x16x32_bf16 v[24:27], v[120:123], v[176:179], v[24:27]
	v_mfma_f32_16x16x32_bf16 v[12:15], v[112:115], v[208:211], v[12:15]
	v_mfma_f32_16x16x32_bf16 v[8:11], v[120:123], v[208:211], v[8:11]
	v_mfma_f32_16x16x32_bf16 v[60:63], v[116:119], v[148:151], v[60:63]
	v_mfma_f32_16x16x32_bf16 v[56:59], v[124:127], v[148:151], v[56:59]
	v_mfma_f32_16x16x32_bf16 v[44:47], v[116:119], v[156:159], v[44:47]
	v_mfma_f32_16x16x32_bf16 v[40:43], v[124:127], v[156:159], v[40:43]
	v_mfma_f32_16x16x32_bf16 v[28:31], v[116:119], v[180:183], v[28:31]
	v_mfma_f32_16x16x32_bf16 v[24:27], v[124:127], v[180:183], v[24:27]
	v_mfma_f32_16x16x32_bf16 v[12:15], v[116:119], v[212:215], v[12:15]
	v_mfma_f32_16x16x32_bf16 v[8:11], v[124:127], v[212:215], v[8:11]
	s_setprio 0
	s_setprio 1
	v_mfma_f32_16x16x32_bf16 v[52:55], v[128:131], v[144:147], v[52:55]
	v_mfma_f32_16x16x32_bf16 v[48:51], v[136:139], v[144:147], v[48:51]
	v_mfma_f32_16x16x32_bf16 v[36:39], v[128:131], v[152:155], v[36:39]
	v_mfma_f32_16x16x32_bf16 v[32:35], v[136:139], v[152:155], v[32:35]
	v_mfma_f32_16x16x32_bf16 v[20:23], v[128:131], v[176:179], v[20:23]
	v_mfma_f32_16x16x32_bf16 v[16:19], v[136:139], v[176:179], v[16:19]
	v_mfma_f32_16x16x32_bf16 v[4:7], v[128:131], v[208:211], v[4:7]
	v_mfma_f32_16x16x32_bf16 v[0:3], v[136:139], v[208:211], v[0:3]
	v_mfma_f32_16x16x32_bf16 v[52:55], v[132:135], v[148:151], v[52:55]
	v_mfma_f32_16x16x32_bf16 v[48:51], v[140:143], v[148:151], v[48:51]
	v_mfma_f32_16x16x32_bf16 v[36:39], v[132:135], v[156:159], v[36:39]
	v_mfma_f32_16x16x32_bf16 v[32:35], v[140:143], v[156:159], v[32:35]
	v_mfma_f32_16x16x32_bf16 v[20:23], v[132:135], v[180:183], v[20:23]
	v_mfma_f32_16x16x32_bf16 v[16:19], v[140:143], v[180:183], v[16:19]
	v_mfma_f32_16x16x32_bf16 v[4:7], v[132:135], v[212:215], v[4:7]
	v_mfma_f32_16x16x32_bf16 v[0:3], v[140:143], v[212:215], v[0:3]
	s_setprio 0
	s_barrier
	s_add_i32 s55, s55, 2
	s_add_u32 s44, s44, 0x100
	s_addc_u32 s45, s45, 0
	s_cmp_gt_u32 s55, 41
	s_mov_b64 s[12:13], s[14:15]
	s_cbranch_scc0 .LBB0_1479
	s_and_b64 vcc, exec, s[8:9]
	s_cbranch_vccz .LBB0_1482
	s_barrier
